# + K-loop LDS-DMA loads use scalar-base + 32-bit lane offset addressing (drops 16 64-bit VALU adds per iteration per wave) in 5 GEMM loops
# speedup vs baseline: 1.0174x; 1.0073x over previous
; #define PG8_STAGE(bufoff, gbase, voff) do { _Pragma("unroll") for (int _i = 0; _i < 2; ++_i) \
;         __builtin_amdgcn_global_load_lds((const unsigned*)((const char*)(gbase) + (voff)[_i]), (PG8_LAS unsigned*)(lds + (bufoff) + ldsw + _i * 8192), 16, 0, 0); } while (0)
; #define PG8_LDA(dst, b, h) do { _Pragma("unroll") for (int m = 0; m < 4; ++m) _Pragma("unroll") for (int k = 0; k < 2; ++k) dst[m][k] = *(const PG8_LAS bf16x8*)(lds + PG8_SA(b, h) + aoff + m * 2048 + k * 1024); } while (0)
; #define PG8_LDB(dst, b, h) do { _Pragma("unroll") for (int n = 0; n < 2; ++n) _Pragma("unroll") for (int k = 0; k < 2; ++k) dst[n][k] = *(const PG8_LAS bf16x8*)(lds + PG8_SB(b, h) + boff + n * 2048 + k * 1024); } while (0)
; #define PG8_WAIT_V(n) asm volatile("s_waitcnt vmcnt(" #n ")" ::: "memory")
; #define PG8_WAIT_L(n) asm volatile("s_waitcnt lgkmcnt(" #n ")" ::: "memory")
; #define PG8_BAR __builtin_amdgcn_s_barrier()
; template <class Epi, class Sched, bool ALIGN_EPI = false, bool SP2 = false, bool F8 = false>
; __device__ __forceinline__ void gemm_phase(PG8_LAS unsigned char* lds, const int K, const Sched& S, const Epi& E, const int wave) {
;     ...
;             const bool last = (t == nt - 2);
;             const char* a1 = cA + (size_t)(t + 1) * kstep;
;             const char* a2 = last ? nA : cA + (size_t)(t + 2) * kstep; const char* b2 = last ? nB : cB + (size_t)(t + 2) * kstep;
;             const char* a3 = a2 + kstep; const char* b3 = b2 + kstep;
;             asm volatile("" : "+s"(a1), "+s"(a2), "+s"(b2), "+s"(a3), "+s"(b3));
;             if (last && has_next) S.a_ready(nxt);
;             if constexpr (Epi::KHOOK) { if (cur.prob == 2 ? (t == 16) : (t == 32 || t == 48)) { if (wr == 0) PG8_BAR;
;                 E.khook(acc, cur, (cur.prob == 2 || t == 48) ? 1 : 0, wr, wc, fr, fq); if (wr == 1) PG8_BAR; } }
;             if constexpr (SP2) {
;             PG8_LDB(B0, 0, 0); PG8_LDB(B1, 0, 1); PG8_SCHED; PG8_LDA(At, 0, 0); PG8_STAGE(PG8_SA(1, 1), a1 + hstep, voffA);
;             PG8_WAIT_V(8); PG8_WAIT_L(0); PG8_BAR; PG8_MMA(0, 0, At, B0); PG8_MMA(0, 1, At, B1); PG8_BAR; PG8_SCHED;
;             PG8_LDA(At, 0, 1); PG8_STAGE(PG8_SB(0, 0), b2, voffB); PG8_STAGE(PG8_SB(0, 1), b2 + hstep, voffB); PG8_STAGE(PG8_SA(0, 0), a2, voffA);
;             PG8_WAIT_V(8); PG8_WAIT_L(0); PG8_BAR; PG8_MMA(1, 0, At, B0); PG8_MMA(1, 1, At, B1); PG8_BAR; PG8_SCHED;
.Lpeel_k186:
	s_add_u32 s6, s14, s0
	s_addc_u32 s7, s15, s1
	s_add_u32 s64, s6, 0xffffff80
	s_addc_u32 s65, s7, -1
	s_add_u32 s76, s36, s0
	s_addc_u32 s77, s37, s1
	s_cmp_eq_u32 vcc_lo, 60
	s_cselect_b32 s94, s85, s6
	s_cselect_b32 s95, s83, s7
	s_cselect_b32 s7, s96, s77
	s_cselect_b32 s6, s97, s76
	s_add_u32 s78, s94, 0x80
	s_addc_u32 s79, s95, 0
	s_add_u32 s76, s6, 0x80
	s_addc_u32 s77, s7, 0
	v_add_u32_e32 v140, s47, v245
	v_add_u32_e32 v156, s41, v245
	ds_read_b128 v[128:131], v140
	ds_read_b128 v[132:135], v140 offset:1024
	ds_read_b128 v[136:139], v140 offset:2048
	ds_read_b128 v[140:143], v140 offset:3072
	ds_read_b128 v[144:147], v156
	ds_read_b128 v[148:151], v156 offset:1024
	ds_read_b128 v[152:155], v156 offset:2048
	ds_read_b128 v[156:159], v156 offset:3072
	s_add_u32 s64, s64, 0x100000
	s_addc_u32 s65, s65, 0
	s_add_i32 m0, s13, 0xc000
	ds_read_b128 v[160:163], v248
	ds_read_b128 v[164:167], v248 offset:1024
	ds_read_b128 v[168:171], v248 offset:2048
	ds_read_b128 v[172:175], v248 offset:3072
	ds_read_b128 v[176:179], v248 offset:4096
	ds_read_b128 v[180:183], v248 offset:5120
	ds_read_b128 v[184:187], v248 offset:6144
	ds_read_b128 v[188:191], v248 offset:7168
	global_load_lds_dwordx4 v192, s[64:65]
	s_add_i32 m0, s13, 0xe000
	s_nop 0
	global_load_lds_dwordx4 v196, s[64:65]
	s_waitcnt vmcnt(8)
	s_waitcnt lgkmcnt(0)
	s_setprio 1
	s_barrier
	v_mfma_f32_16x16x32_bf16 v[124:127], v[128:131], v[160:163], 0
	v_mfma_f32_16x16x32_bf16 v[120:123], v[136:139], v[160:163], 0
	v_mfma_f32_16x16x32_bf16 v[116:119], v[128:131], v[168:171], 0
	v_mfma_f32_16x16x32_bf16 v[112:115], v[136:139], v[168:171], 0
	v_mfma_f32_16x16x32_bf16 v[108:111], v[128:131], v[176:179], 0
	v_mfma_f32_16x16x32_bf16 v[104:107], v[136:139], v[176:179], 0
	v_mfma_f32_16x16x32_bf16 v[100:103], v[128:131], v[184:187], 0
	v_mfma_f32_16x16x32_bf16 v[96:99], v[136:139], v[184:187], 0
	v_mfma_f32_16x16x32_bf16 v[124:127], v[132:135], v[164:167], v[124:127]
	v_mfma_f32_16x16x32_bf16 v[120:123], v[140:143], v[164:167], v[120:123]
	v_mfma_f32_16x16x32_bf16 v[116:119], v[132:135], v[172:175], v[116:119]
	v_mfma_f32_16x16x32_bf16 v[112:115], v[140:143], v[172:175], v[112:115]
	v_mfma_f32_16x16x32_bf16 v[108:111], v[132:135], v[180:183], v[108:111]
	v_mfma_f32_16x16x32_bf16 v[104:107], v[140:143], v[180:183], v[104:107]
	v_mfma_f32_16x16x32_bf16 v[100:103], v[132:135], v[188:191], v[100:103]
	v_mfma_f32_16x16x32_bf16 v[96:99], v[140:143], v[188:191], v[96:99]
	v_mfma_f32_16x16x32_bf16 v[92:95], v[144:147], v[160:163], 0
	v_mfma_f32_16x16x32_bf16 v[88:91], v[152:155], v[160:163], 0
	v_mfma_f32_16x16x32_bf16 v[84:87], v[144:147], v[168:171], 0
	v_mfma_f32_16x16x32_bf16 v[80:83], v[152:155], v[168:171], 0
	v_mfma_f32_16x16x32_bf16 v[76:79], v[144:147], v[176:179], 0
	v_mfma_f32_16x16x32_bf16 v[72:75], v[152:155], v[176:179], 0
	v_mfma_f32_16x16x32_bf16 v[68:71], v[144:147], v[184:187], 0
	v_mfma_f32_16x16x32_bf16 v[64:67], v[152:155], v[184:187], 0
	v_mfma_f32_16x16x32_bf16 v[92:95], v[148:151], v[164:167], v[92:95]
	v_mfma_f32_16x16x32_bf16 v[88:91], v[156:159], v[164:167], v[88:91]
	v_mfma_f32_16x16x32_bf16 v[84:87], v[148:151], v[172:175], v[84:87]
	v_mfma_f32_16x16x32_bf16 v[80:83], v[156:159], v[172:175], v[80:83]
	v_mfma_f32_16x16x32_bf16 v[76:79], v[148:151], v[180:183], v[76:79]
	v_mfma_f32_16x16x32_bf16 v[72:75], v[156:159], v[180:183], v[72:75]
	v_mfma_f32_16x16x32_bf16 v[68:71], v[148:151], v[188:191], v[68:71]
	v_mfma_f32_16x16x32_bf16 v[64:67], v[156:159], v[188:191], v[64:67]
	s_barrier
	s_setprio 0
	s_add_i32 s64, s47, s74
	s_mov_b32 m0, s64
	ds_read_b128 v[160:163], v248 offset:16384
	ds_read_b128 v[164:167], v248 offset:17408
	ds_read_b128 v[168:171], v248 offset:18432
	ds_read_b128 v[172:175], v248 offset:19456
	ds_read_b128 v[176:179], v248 offset:20480
	ds_read_b128 v[180:183], v248 offset:21504
	ds_read_b128 v[184:187], v248 offset:22528
	ds_read_b128 v[188:191], v248 offset:23552
	global_load_lds_dwordx4 v194, s[6:7]
	s_add_i32 m0, s64, 0x2000
	s_nop 0
	global_load_lds_dwordx4 v198, s[6:7]
	s_add_u32 s6, s6, 0x100000
	s_addc_u32 s7, s7, 0
	s_add_i32 s64, s41, s74
	s_mov_b32 m0, s64
	s_nop 0
	global_load_lds_dwordx4 v194, s[6:7]
	s_add_i32 m0, s64, 0x2000
	s_nop 0
	global_load_lds_dwordx4 v198, s[6:7]
	s_mov_b32 m0, s13
	s_nop 0
	global_load_lds_dwordx4 v192, s[94:95]
	s_mov_b32 m0, s51
	s_nop 0
	global_load_lds_dwordx4 v196, s[94:95]
	s_waitcnt vmcnt(8)
	s_waitcnt lgkmcnt(0)
	s_setprio 1
	s_barrier
	v_mfma_f32_16x16x32_bf16 v[60:63], v[128:131], v[160:163], 0
	v_mfma_f32_16x16x32_bf16 v[56:59], v[136:139], v[160:163], 0
	v_mfma_f32_16x16x32_bf16 v[52:55], v[128:131], v[168:171], 0
	v_mfma_f32_16x16x32_bf16 v[48:51], v[136:139], v[168:171], 0
	v_mfma_f32_16x16x32_bf16 v[44:47], v[128:131], v[176:179], 0
	v_mfma_f32_16x16x32_bf16 v[40:43], v[136:139], v[176:179], 0
	v_mfma_f32_16x16x32_bf16 v[36:39], v[128:131], v[184:187], 0
	v_mfma_f32_16x16x32_bf16 v[32:35], v[136:139], v[184:187], 0
	v_mfma_f32_16x16x32_bf16 v[60:63], v[132:135], v[164:167], v[60:63]
	v_mfma_f32_16x16x32_bf16 v[56:59], v[140:143], v[164:167], v[56:59]
	v_mfma_f32_16x16x32_bf16 v[52:55], v[132:135], v[172:175], v[52:55]
	v_mfma_f32_16x16x32_bf16 v[48:51], v[140:143], v[172:175], v[48:51]
	v_mfma_f32_16x16x32_bf16 v[44:47], v[132:135], v[180:183], v[44:47]
	v_mfma_f32_16x16x32_bf16 v[40:43], v[140:143], v[180:183], v[40:43]
	v_mfma_f32_16x16x32_bf16 v[36:39], v[132:135], v[188:191], v[36:39]
	v_mfma_f32_16x16x32_bf16 v[32:35], v[140:143], v[188:191], v[32:35]
	v_mfma_f32_16x16x32_bf16 v[28:31], v[144:147], v[160:163], 0
	v_mfma_f32_16x16x32_bf16 v[24:27], v[152:155], v[160:163], 0
	v_mfma_f32_16x16x32_bf16 v[20:23], v[144:147], v[168:171], 0
	v_mfma_f32_16x16x32_bf16 v[16:19], v[152:155], v[168:171], 0
	v_mfma_f32_16x16x32_bf16 v[12:15], v[144:147], v[176:179], 0
	v_mfma_f32_16x16x32_bf16 v[8:11], v[152:155], v[176:179], 0
	v_mfma_f32_16x16x32_bf16 v[4:7], v[144:147], v[184:187], 0
	v_mfma_f32_16x16x32_bf16 v[0:3], v[152:155], v[184:187], 0
	v_mfma_f32_16x16x32_bf16 v[28:31], v[148:151], v[164:167], v[28:31]
	v_mfma_f32_16x16x32_bf16 v[24:27], v[156:159], v[164:167], v[24:27]
	v_mfma_f32_16x16x32_bf16 v[20:23], v[148:151], v[172:175], v[20:23]
	v_mfma_f32_16x16x32_bf16 v[16:19], v[156:159], v[172:175], v[16:19]
	v_mfma_f32_16x16x32_bf16 v[12:15], v[148:151], v[180:183], v[12:15]
	v_mfma_f32_16x16x32_bf16 v[8:11], v[156:159], v[180:183], v[8:11]
	v_mfma_f32_16x16x32_bf16 v[4:7], v[148:151], v[188:191], v[4:7]
	v_mfma_f32_16x16x32_bf16 v[0:3], v[156:159], v[188:191], v[0:3]
	s_barrier
	s_branch .Lmid_k186
; #define PG8_STAGE(bufoff, gbase, voff) do { _Pragma("unroll") for (int _i = 0; _i < 2; ++_i) \
;         __builtin_amdgcn_global_load_lds((const unsigned*)((const char*)(gbase) + (voff)[_i]), (PG8_LAS unsigned*)(lds + (bufoff) + ldsw + _i * 8192), 16, 0, 0); } while (0)
; #define PG8_LDA(dst, b, h) do { _Pragma("unroll") for (int m = 0; m < 4; ++m) _Pragma("unroll") for (int k = 0; k < 2; ++k) dst[m][k] = *(const PG8_LAS bf16x8*)(lds + PG8_SA(b, h) + aoff + m * 2048 + k * 1024); } while (0)
; #define PG8_LDB(dst, b, h) do { _Pragma("unroll") for (int n = 0; n < 2; ++n) _Pragma("unroll") for (int k = 0; k < 2; ++k) dst[n][k] = *(const PG8_LAS bf16x8*)(lds + PG8_SB(b, h) + boff + n * 2048 + k * 1024); } while (0)
; #define PG8_WAIT_V(n) asm volatile("s_waitcnt vmcnt(" #n ")" ::: "memory")
; #define PG8_WAIT_L(n) asm volatile("s_waitcnt lgkmcnt(" #n ")" ::: "memory")
; #define PG8_BAR __builtin_amdgcn_s_barrier()
; template <class Epi, class Sched, bool ALIGN_EPI = false, bool SP2 = false, bool F8 = false>
; __device__ __forceinline__ void gemm_phase(PG8_LAS unsigned char* lds, const int K, const Sched& S, const Epi& E, const int wave) {
;     ...
;             const bool last = (t == nt - 2);
;             const char* a1 = cA + (size_t)(t + 1) * kstep;
;             const char* a2 = last ? nA : cA + (size_t)(t + 2) * kstep; const char* b2 = last ? nB : cB + (size_t)(t + 2) * kstep;
;             const char* a3 = a2 + kstep; const char* b3 = b2 + kstep;
;             asm volatile("" : "+s"(a1), "+s"(a2), "+s"(b2), "+s"(a3), "+s"(b3));
;             if (last && has_next) S.a_ready(nxt);
;             if constexpr (Epi::KHOOK) { if (cur.prob == 2 ? (t == 16) : (t == 32 || t == 48)) { if (wr == 0) PG8_BAR;
;                 E.khook(acc, cur, (cur.prob == 2 || t == 48) ? 1 : 0, wr, wc, fr, fq); if (wr == 1) PG8_BAR; } }
;             if constexpr (SP2) {
;             PG8_LDB(B0, 0, 0); PG8_LDB(B1, 0, 1); PG8_SCHED; PG8_LDA(At, 0, 0); PG8_STAGE(PG8_SA(1, 1), a1 + hstep, voffA);
;             PG8_WAIT_V(8); PG8_WAIT_L(0); PG8_BAR; PG8_MMA(0, 0, At, B0); PG8_MMA(0, 1, At, B1); PG8_BAR; PG8_SCHED;
;             PG8_LDA(At, 0, 1); PG8_STAGE(PG8_SB(0, 0), b2, voffB); PG8_STAGE(PG8_SB(0, 1), b2 + hstep, voffB); PG8_STAGE(PG8_SA(0, 0), a2, voffA);
;             PG8_WAIT_V(8); PG8_WAIT_L(0); PG8_BAR; PG8_MMA(1, 0, At, B0); PG8_MMA(1, 1, At, B1); PG8_BAR; PG8_SCHED;
.LBB0_186:
	s_add_u32 s6, s14, s0
	s_addc_u32 s7, s15, s1
	s_add_u32 s64, s6, 0xffffff80
	s_addc_u32 s65, s7, -1
	s_add_u32 s76, s36, s0
	s_addc_u32 s77, s37, s1
	s_cmp_eq_u32 vcc_lo, 60
	s_cselect_b32 s94, s85, s6
	s_cselect_b32 s95, s83, s7
	s_cselect_b32 s7, s96, s77
	s_cselect_b32 s6, s97, s76
	s_add_u32 s78, s94, 0x80
	s_addc_u32 s79, s95, 0
	s_add_u32 s76, s6, 0x80
	s_addc_u32 s77, s7, 0
	v_add_u32_e32 v140, s47, v245
	v_add_u32_e32 v156, s41, v245
	ds_read_b128 v[128:131], v140
	ds_read_b128 v[132:135], v140 offset:1024
	ds_read_b128 v[136:139], v140 offset:2048
	ds_read_b128 v[140:143], v140 offset:3072
	ds_read_b128 v[144:147], v156
	ds_read_b128 v[148:151], v156 offset:1024
	ds_read_b128 v[152:155], v156 offset:2048
	ds_read_b128 v[156:159], v156 offset:3072
	s_add_u32 s64, s64, 0x100000
	s_addc_u32 s65, s65, 0
	s_add_i32 m0, s13, 0xc000
	ds_read_b128 v[160:163], v248
	ds_read_b128 v[164:167], v248 offset:1024
	ds_read_b128 v[168:171], v248 offset:2048
	ds_read_b128 v[172:175], v248 offset:3072
	ds_read_b128 v[176:179], v248 offset:4096
	ds_read_b128 v[180:183], v248 offset:5120
	ds_read_b128 v[184:187], v248 offset:6144
	ds_read_b128 v[188:191], v248 offset:7168
	global_load_lds_dwordx4 v192, s[64:65]
	s_add_i32 m0, s13, 0xe000
	s_nop 0
	global_load_lds_dwordx4 v196, s[64:65]
	s_waitcnt vmcnt(8)
	s_waitcnt lgkmcnt(0)
	s_setprio 1
	s_barrier
	v_mfma_f32_16x16x32_bf16 v[124:127], v[128:131], v[160:163], v[124:127]
	v_mfma_f32_16x16x32_bf16 v[120:123], v[136:139], v[160:163], v[120:123]
	v_mfma_f32_16x16x32_bf16 v[116:119], v[128:131], v[168:171], v[116:119]
	v_mfma_f32_16x16x32_bf16 v[112:115], v[136:139], v[168:171], v[112:115]
	v_mfma_f32_16x16x32_bf16 v[108:111], v[128:131], v[176:179], v[108:111]
	v_mfma_f32_16x16x32_bf16 v[104:107], v[136:139], v[176:179], v[104:107]
	v_mfma_f32_16x16x32_bf16 v[100:103], v[128:131], v[184:187], v[100:103]
	v_mfma_f32_16x16x32_bf16 v[96:99], v[136:139], v[184:187], v[96:99]
	v_mfma_f32_16x16x32_bf16 v[124:127], v[132:135], v[164:167], v[124:127]
	v_mfma_f32_16x16x32_bf16 v[120:123], v[140:143], v[164:167], v[120:123]
	v_mfma_f32_16x16x32_bf16 v[116:119], v[132:135], v[172:175], v[116:119]
	v_mfma_f32_16x16x32_bf16 v[112:115], v[140:143], v[172:175], v[112:115]
	v_mfma_f32_16x16x32_bf16 v[108:111], v[132:135], v[180:183], v[108:111]
	v_mfma_f32_16x16x32_bf16 v[104:107], v[140:143], v[180:183], v[104:107]
	v_mfma_f32_16x16x32_bf16 v[100:103], v[132:135], v[188:191], v[100:103]
	v_mfma_f32_16x16x32_bf16 v[96:99], v[140:143], v[188:191], v[96:99]
	v_mfma_f32_16x16x32_bf16 v[92:95], v[144:147], v[160:163], v[92:95]
	v_mfma_f32_16x16x32_bf16 v[88:91], v[152:155], v[160:163], v[88:91]
	v_mfma_f32_16x16x32_bf16 v[84:87], v[144:147], v[168:171], v[84:87]
	v_mfma_f32_16x16x32_bf16 v[80:83], v[152:155], v[168:171], v[80:83]
	v_mfma_f32_16x16x32_bf16 v[76:79], v[144:147], v[176:179], v[76:79]
	v_mfma_f32_16x16x32_bf16 v[72:75], v[152:155], v[176:179], v[72:75]
	v_mfma_f32_16x16x32_bf16 v[68:71], v[144:147], v[184:187], v[68:71]
	v_mfma_f32_16x16x32_bf16 v[64:67], v[152:155], v[184:187], v[64:67]
	v_mfma_f32_16x16x32_bf16 v[92:95], v[148:151], v[164:167], v[92:95]
	v_mfma_f32_16x16x32_bf16 v[88:91], v[156:159], v[164:167], v[88:91]
	v_mfma_f32_16x16x32_bf16 v[84:87], v[148:151], v[172:175], v[84:87]
	v_mfma_f32_16x16x32_bf16 v[80:83], v[156:159], v[172:175], v[80:83]
	v_mfma_f32_16x16x32_bf16 v[76:79], v[148:151], v[180:183], v[76:79]
	v_mfma_f32_16x16x32_bf16 v[72:75], v[156:159], v[180:183], v[72:75]
	v_mfma_f32_16x16x32_bf16 v[68:71], v[148:151], v[188:191], v[68:71]
	v_mfma_f32_16x16x32_bf16 v[64:67], v[156:159], v[188:191], v[64:67]
	s_barrier
	s_setprio 0
	s_add_i32 s64, s47, s74
	s_mov_b32 m0, s64
	ds_read_b128 v[160:163], v248 offset:16384
	ds_read_b128 v[164:167], v248 offset:17408
	ds_read_b128 v[168:171], v248 offset:18432
	ds_read_b128 v[172:175], v248 offset:19456
	ds_read_b128 v[176:179], v248 offset:20480
	ds_read_b128 v[180:183], v248 offset:21504
	ds_read_b128 v[184:187], v248 offset:22528
	ds_read_b128 v[188:191], v248 offset:23552
	global_load_lds_dwordx4 v194, s[6:7]
	s_add_i32 m0, s64, 0x2000
	s_nop 0
	global_load_lds_dwordx4 v198, s[6:7]
	s_add_u32 s6, s6, 0x100000
	s_addc_u32 s7, s7, 0
	s_add_i32 s64, s41, s74
	s_mov_b32 m0, s64
	s_nop 0
	global_load_lds_dwordx4 v194, s[6:7]
	s_add_i32 m0, s64, 0x2000
	s_nop 0
	global_load_lds_dwordx4 v198, s[6:7]
	s_mov_b32 m0, s13
	s_nop 0
	global_load_lds_dwordx4 v192, s[94:95]
	s_mov_b32 m0, s51
	s_nop 0
	global_load_lds_dwordx4 v196, s[94:95]
	s_waitcnt vmcnt(8)
	s_waitcnt lgkmcnt(0)
	s_setprio 1
	s_barrier
	v_mfma_f32_16x16x32_bf16 v[60:63], v[128:131], v[160:163], v[60:63]
	v_mfma_f32_16x16x32_bf16 v[56:59], v[136:139], v[160:163], v[56:59]
	v_mfma_f32_16x16x32_bf16 v[52:55], v[128:131], v[168:171], v[52:55]
	v_mfma_f32_16x16x32_bf16 v[48:51], v[136:139], v[168:171], v[48:51]
	v_mfma_f32_16x16x32_bf16 v[44:47], v[128:131], v[176:179], v[44:47]
	v_mfma_f32_16x16x32_bf16 v[40:43], v[136:139], v[176:179], v[40:43]
	v_mfma_f32_16x16x32_bf16 v[36:39], v[128:131], v[184:187], v[36:39]
	v_mfma_f32_16x16x32_bf16 v[32:35], v[136:139], v[184:187], v[32:35]
	v_mfma_f32_16x16x32_bf16 v[60:63], v[132:135], v[164:167], v[60:63]
	v_mfma_f32_16x16x32_bf16 v[56:59], v[140:143], v[164:167], v[56:59]
	v_mfma_f32_16x16x32_bf16 v[52:55], v[132:135], v[172:175], v[52:55]
	v_mfma_f32_16x16x32_bf16 v[48:51], v[140:143], v[172:175], v[48:51]
	v_mfma_f32_16x16x32_bf16 v[44:47], v[132:135], v[180:183], v[44:47]
	v_mfma_f32_16x16x32_bf16 v[40:43], v[140:143], v[180:183], v[40:43]
	v_mfma_f32_16x16x32_bf16 v[36:39], v[132:135], v[188:191], v[36:39]
	v_mfma_f32_16x16x32_bf16 v[32:35], v[140:143], v[188:191], v[32:35]
	v_mfma_f32_16x16x32_bf16 v[28:31], v[144:147], v[160:163], v[28:31]
	v_mfma_f32_16x16x32_bf16 v[24:27], v[152:155], v[160:163], v[24:27]
	v_mfma_f32_16x16x32_bf16 v[20:23], v[144:147], v[168:171], v[20:23]
	v_mfma_f32_16x16x32_bf16 v[16:19], v[152:155], v[168:171], v[16:19]
	v_mfma_f32_16x16x32_bf16 v[12:15], v[144:147], v[176:179], v[12:15]
	v_mfma_f32_16x16x32_bf16 v[8:11], v[152:155], v[176:179], v[8:11]
	v_mfma_f32_16x16x32_bf16 v[4:7], v[144:147], v[184:187], v[4:7]
	v_mfma_f32_16x16x32_bf16 v[0:3], v[152:155], v[184:187], v[0:3]
	v_mfma_f32_16x16x32_bf16 v[28:31], v[148:151], v[164:167], v[28:31]
	v_mfma_f32_16x16x32_bf16 v[24:27], v[156:159], v[164:167], v[24:27]
	v_mfma_f32_16x16x32_bf16 v[20:23], v[148:151], v[172:175], v[20:23]
	v_mfma_f32_16x16x32_bf16 v[16:19], v[156:159], v[172:175], v[16:19]
	v_mfma_f32_16x16x32_bf16 v[12:15], v[148:151], v[180:183], v[12:15]
	v_mfma_f32_16x16x32_bf16 v[8:11], v[156:159], v[180:183], v[8:11]
	v_mfma_f32_16x16x32_bf16 v[4:7], v[148:151], v[188:191], v[4:7]
	v_mfma_f32_16x16x32_bf16 v[0:3], v[156:159], v[188:191], v[0:3]
	s_barrier
; #define PG8_STAGE(bufoff, gbase, voff) do { _Pragma("unroll") for (int _i = 0; _i < 2; ++_i) \
;         __builtin_amdgcn_global_load_lds((const unsigned*)((const char*)(gbase) + (voff)[_i]), (PG8_LAS unsigned*)(lds + (bufoff) + ldsw + _i * 8192), 16, 0, 0); } while (0)
; #define PG8_LDA(dst, b, h) do { _Pragma("unroll") for (int m = 0; m < 4; ++m) _Pragma("unroll") for (int k = 0; k < 2; ++k) dst[m][k] = *(const PG8_LAS bf16x8*)(lds + PG8_SA(b, h) + aoff + m * 2048 + k * 1024); } while (0)
; #define PG8_LDB(dst, b, h) do { _Pragma("unroll") for (int n = 0; n < 2; ++n) _Pragma("unroll") for (int k = 0; k < 2; ++k) dst[n][k] = *(const PG8_LAS bf16x8*)(lds + PG8_SB(b, h) + boff + n * 2048 + k * 1024); } while (0)
; #define PG8_WAIT_V(n) asm volatile("s_waitcnt vmcnt(" #n ")" ::: "memory")
; #define PG8_WAIT_L(n) asm volatile("s_waitcnt lgkmcnt(" #n ")" ::: "memory")
; #define PG8_BAR __builtin_amdgcn_s_barrier()
; #define PG8_SCHED __builtin_amdgcn_sched_barrier(0)
; template <class Epi, class Sched, bool ALIGN_EPI = false, bool SP2 = false, bool F8 = false>
; __device__ __forceinline__ void gemm_phase(PG8_LAS unsigned char* lds, const int K, const Sched& S, const Epi& E, const int wave) {
;     ...
;             PG8_LDB(B0, 1, 0); PG8_LDB(B1, 1, 1); PG8_SCHED; PG8_LDA(At, 1, 0); PG8_STAGE(PG8_SA(0, 1), a2 + hstep, voffA);
;             PG8_WAIT_V(8); PG8_WAIT_L(0); PG8_BAR; PG8_MMA(0, 0, At, B0); PG8_MMA(0, 1, At, B1); PG8_BAR; PG8_SCHED;
;             PG8_LDA(At, 1, 1); PG8_STAGE(PG8_SB(1, 0), b3, voffB); PG8_STAGE(PG8_SB(1, 1), b3 + hstep, voffB); PG8_STAGE(PG8_SA(1, 0), a3, voffA);
;             PG8_WAIT_V(8); PG8_WAIT_L(0); PG8_BAR; PG8_MMA(1, 0, At, B0); PG8_MMA(1, 1, At, B1); PG8_BAR; PG8_SCHED;
.Lmid_k186:
	s_setprio 0
	s_add_i32 s64, 0, 0x18000
	s_add_i32 s65, 0, 0x1c000
	v_add_u32_e32 v140, s64, v245
	v_add_u32_e32 v156, s65, v245
	ds_read_b128 v[128:131], v140
	ds_read_b128 v[132:135], v140 offset:1024
	ds_read_b128 v[136:139], v140 offset:2048
	ds_read_b128 v[140:143], v140 offset:3072
	ds_read_b128 v[144:147], v156
	ds_read_b128 v[148:151], v156 offset:1024
	ds_read_b128 v[152:155], v156 offset:2048
	ds_read_b128 v[156:159], v156 offset:3072
	s_add_u32 s6, s94, 0x100000
	s_addc_u32 s7, s95, 0
	s_mov_b32 m0, s75
	ds_read_b128 v[160:163], v248 offset:32768
	ds_read_b128 v[164:167], v248 offset:33792
	ds_read_b128 v[168:171], v248 offset:34816
	ds_read_b128 v[172:175], v248 offset:35840
	ds_read_b128 v[176:179], v248 offset:36864
	ds_read_b128 v[180:183], v248 offset:37888
	ds_read_b128 v[184:187], v248 offset:38912
	ds_read_b128 v[188:191], v248 offset:39936
	global_load_lds_dwordx4 v192, s[6:7]
	s_mov_b32 m0, s48
	s_nop 0
	global_load_lds_dwordx4 v196, s[6:7]
	s_waitcnt vmcnt(8)
	s_waitcnt lgkmcnt(0)
	s_setprio 1
	s_barrier
	v_mfma_f32_16x16x32_bf16 v[124:127], v[128:131], v[160:163], v[124:127]
	v_mfma_f32_16x16x32_bf16 v[120:123], v[136:139], v[160:163], v[120:123]
	v_mfma_f32_16x16x32_bf16 v[116:119], v[128:131], v[168:171], v[116:119]
	v_mfma_f32_16x16x32_bf16 v[112:115], v[136:139], v[168:171], v[112:115]
	v_mfma_f32_16x16x32_bf16 v[108:111], v[128:131], v[176:179], v[108:111]
	v_mfma_f32_16x16x32_bf16 v[104:107], v[136:139], v[176:179], v[104:107]
	v_mfma_f32_16x16x32_bf16 v[100:103], v[128:131], v[184:187], v[100:103]
	v_mfma_f32_16x16x32_bf16 v[96:99], v[136:139], v[184:187], v[96:99]
	v_mfma_f32_16x16x32_bf16 v[124:127], v[132:135], v[164:167], v[124:127]
	v_mfma_f32_16x16x32_bf16 v[120:123], v[140:143], v[164:167], v[120:123]
	v_mfma_f32_16x16x32_bf16 v[116:119], v[132:135], v[172:175], v[116:119]
	v_mfma_f32_16x16x32_bf16 v[112:115], v[140:143], v[172:175], v[112:115]
	v_mfma_f32_16x16x32_bf16 v[108:111], v[132:135], v[180:183], v[108:111]
	v_mfma_f32_16x16x32_bf16 v[104:107], v[140:143], v[180:183], v[104:107]
	v_mfma_f32_16x16x32_bf16 v[100:103], v[132:135], v[188:191], v[100:103]
	v_mfma_f32_16x16x32_bf16 v[96:99], v[140:143], v[188:191], v[96:99]
	v_mfma_f32_16x16x32_bf16 v[92:95], v[144:147], v[160:163], v[92:95]
	v_mfma_f32_16x16x32_bf16 v[88:91], v[152:155], v[160:163], v[88:91]
	v_mfma_f32_16x16x32_bf16 v[84:87], v[144:147], v[168:171], v[84:87]
	v_mfma_f32_16x16x32_bf16 v[80:83], v[152:155], v[168:171], v[80:83]
	v_mfma_f32_16x16x32_bf16 v[76:79], v[144:147], v[176:179], v[76:79]
	v_mfma_f32_16x16x32_bf16 v[72:75], v[152:155], v[176:179], v[72:75]
	v_mfma_f32_16x16x32_bf16 v[68:71], v[144:147], v[184:187], v[68:71]
	v_mfma_f32_16x16x32_bf16 v[64:67], v[152:155], v[184:187], v[64:67]
	v_mfma_f32_16x16x32_bf16 v[92:95], v[148:151], v[164:167], v[92:95]
	v_mfma_f32_16x16x32_bf16 v[88:91], v[156:159], v[164:167], v[88:91]
	v_mfma_f32_16x16x32_bf16 v[84:87], v[148:151], v[172:175], v[84:87]
	v_mfma_f32_16x16x32_bf16 v[80:83], v[156:159], v[172:175], v[80:83]
	v_mfma_f32_16x16x32_bf16 v[76:79], v[148:151], v[180:183], v[76:79]
	v_mfma_f32_16x16x32_bf16 v[72:75], v[156:159], v[180:183], v[72:75]
	v_mfma_f32_16x16x32_bf16 v[68:71], v[148:151], v[188:191], v[68:71]
	v_mfma_f32_16x16x32_bf16 v[64:67], v[156:159], v[188:191], v[64:67]
	s_barrier
	s_setprio 0
	s_add_i32 s6, s64, s74
	s_mov_b32 m0, s6
	ds_read_b128 v[160:163], v248 offset:49152
	ds_read_b128 v[164:167], v248 offset:50176
	ds_read_b128 v[168:171], v248 offset:51200
	ds_read_b128 v[172:175], v248 offset:52224
	ds_read_b128 v[176:179], v248 offset:53248
	ds_read_b128 v[180:183], v248 offset:54272
	ds_read_b128 v[184:187], v248 offset:55296
	ds_read_b128 v[188:191], v248 offset:56320
	global_load_lds_dwordx4 v194, s[76:77]
	s_add_i32 m0, s6, 0x2000
	s_add_u32 s6, s76, 0x100000
	s_addc_u32 s7, s77, 0
	s_add_i32 s64, s65, s74
	global_load_lds_dwordx4 v198, s[76:77]
	s_mov_b32 m0, s64
	s_nop 0
	global_load_lds_dwordx4 v194, s[6:7]
	s_add_i32 m0, s64, 0x2000
	s_nop 0
	global_load_lds_dwordx4 v198, s[6:7]
	s_mov_b32 m0, s43
	s_nop 0
	global_load_lds_dwordx4 v192, s[78:79]
	s_mov_b32 m0, s44
	s_nop 0
	global_load_lds_dwordx4 v196, s[78:79]
	s_waitcnt vmcnt(8)
	s_waitcnt lgkmcnt(0)
	s_setprio 1
	s_barrier
	v_mfma_f32_16x16x32_bf16 v[60:63], v[128:131], v[160:163], v[60:63]
	v_mfma_f32_16x16x32_bf16 v[56:59], v[136:139], v[160:163], v[56:59]
	v_mfma_f32_16x16x32_bf16 v[52:55], v[128:131], v[168:171], v[52:55]
	v_mfma_f32_16x16x32_bf16 v[48:51], v[136:139], v[168:171], v[48:51]
	v_mfma_f32_16x16x32_bf16 v[44:47], v[128:131], v[176:179], v[44:47]
	v_mfma_f32_16x16x32_bf16 v[40:43], v[136:139], v[176:179], v[40:43]
	v_mfma_f32_16x16x32_bf16 v[36:39], v[128:131], v[184:187], v[36:39]
	v_mfma_f32_16x16x32_bf16 v[32:35], v[136:139], v[184:187], v[32:35]
	v_mfma_f32_16x16x32_bf16 v[60:63], v[132:135], v[164:167], v[60:63]
	v_mfma_f32_16x16x32_bf16 v[56:59], v[140:143], v[164:167], v[56:59]
	v_mfma_f32_16x16x32_bf16 v[52:55], v[132:135], v[172:175], v[52:55]
	v_mfma_f32_16x16x32_bf16 v[48:51], v[140:143], v[172:175], v[48:51]
	v_mfma_f32_16x16x32_bf16 v[44:47], v[132:135], v[180:183], v[44:47]
	v_mfma_f32_16x16x32_bf16 v[40:43], v[140:143], v[180:183], v[40:43]
	v_mfma_f32_16x16x32_bf16 v[36:39], v[132:135], v[188:191], v[36:39]
	v_mfma_f32_16x16x32_bf16 v[32:35], v[140:143], v[188:191], v[32:35]
	v_mfma_f32_16x16x32_bf16 v[28:31], v[144:147], v[160:163], v[28:31]
	v_mfma_f32_16x16x32_bf16 v[24:27], v[152:155], v[160:163], v[24:27]
	v_mfma_f32_16x16x32_bf16 v[20:23], v[144:147], v[168:171], v[20:23]
	v_mfma_f32_16x16x32_bf16 v[16:19], v[152:155], v[168:171], v[16:19]
	v_mfma_f32_16x16x32_bf16 v[12:15], v[144:147], v[176:179], v[12:15]
	v_mfma_f32_16x16x32_bf16 v[8:11], v[152:155], v[176:179], v[8:11]
	v_mfma_f32_16x16x32_bf16 v[4:7], v[144:147], v[184:187], v[4:7]
	v_mfma_f32_16x16x32_bf16 v[0:3], v[152:155], v[184:187], v[0:3]
	v_mfma_f32_16x16x32_bf16 v[28:31], v[148:151], v[164:167], v[28:31]
	v_mfma_f32_16x16x32_bf16 v[24:27], v[156:159], v[164:167], v[24:27]
	v_mfma_f32_16x16x32_bf16 v[20:23], v[148:151], v[172:175], v[20:23]
	v_mfma_f32_16x16x32_bf16 v[16:19], v[156:159], v[172:175], v[16:19]
	v_mfma_f32_16x16x32_bf16 v[12:15], v[148:151], v[180:183], v[12:15]
	v_mfma_f32_16x16x32_bf16 v[8:11], v[156:159], v[180:183], v[8:11]
	v_mfma_f32_16x16x32_bf16 v[4:7], v[148:151], v[188:191], v[4:7]
	v_mfma_f32_16x16x32_bf16 v[0:3], v[156:159], v[188:191], v[0:3]
	s_barrier
	s_setprio 0
	s_add_i32 vcc_lo, vcc_lo, 2
	s_add_u32 s0, s0, 0x100
	s_addc_u32 s1, s1, 0
	s_cmp_gt_u32 vcc_lo, 61
	s_cbranch_scc0 .LBB0_186
	s_and_b64 vcc, exec, s[80:81]
	s_cbranch_vccz .LBB0_189
	s_barrier

; #define PG8_STAGE(bufoff, gbase, voff) do { _Pragma("unroll") for (int _i = 0; _i < 2; ++_i) \
;         __builtin_amdgcn_global_load_lds((const unsigned*)((const char*)(gbase) + (voff)[_i]), (PG8_LAS unsigned*)(lds + (bufoff) + ldsw + _i * 8192), 16, 0, 0); } while (0)
; #define PG8_LDA(dst, b, h) do { _Pragma("unroll") for (int m = 0; m < 4; ++m) _Pragma("unroll") for (int k = 0; k < 2; ++k) dst[m][k] = *(const PG8_LAS bf16x8*)(lds + PG8_SA(b, h) + aoff + m * 2048 + k * 1024); } while (0)
; #define PG8_LDB(dst, b, h) do { _Pragma("unroll") for (int n = 0; n < 2; ++n) _Pragma("unroll") for (int k = 0; k < 2; ++k) dst[n][k] = *(const PG8_LAS bf16x8*)(lds + PG8_SB(b, h) + boff + n * 2048 + k * 1024); } while (0)
; #define PG8_WAIT_V(n) asm volatile("s_waitcnt vmcnt(" #n ")" ::: "memory")
; #define PG8_WAIT_L(n) asm volatile("s_waitcnt lgkmcnt(" #n ")" ::: "memory")
; #define PG8_BAR __builtin_amdgcn_s_barrier()
; template <class Epi, class Sched, bool ALIGN_EPI = false, bool SP2 = false, bool F8 = false>
; __device__ __forceinline__ void gemm_phase(PG8_LAS unsigned char* lds, const int K, const Sched& S, const Epi& E, const int wave) {
;     ...
;             const bool last = (t == nt - 2);
;             const char* a1 = cA + (size_t)(t + 1) * kstep;
;             const char* a2 = last ? nA : cA + (size_t)(t + 2) * kstep; const char* b2 = last ? nB : cB + (size_t)(t + 2) * kstep;
;             const char* a3 = a2 + kstep; const char* b3 = b2 + kstep;
;             asm volatile("" : "+s"(a1), "+s"(a2), "+s"(b2), "+s"(a3), "+s"(b3));
;             if (last && has_next) S.a_ready(nxt);
;             if constexpr (Epi::KHOOK) { if (cur.prob == 2 ? (t == 16) : (t == 32 || t == 48)) { if (wr == 0) PG8_BAR;
;                 E.khook(acc, cur, (cur.prob == 2 || t == 48) ? 1 : 0, wr, wc, fr, fq); if (wr == 1) PG8_BAR; } }
;             if constexpr (SP2) {
;             PG8_LDB(B0, 0, 0); PG8_LDB(B1, 0, 1); PG8_SCHED; PG8_LDA(At, 0, 0); PG8_STAGE(PG8_SA(1, 1), a1 + hstep, voffA);
;             PG8_WAIT_V(8); PG8_WAIT_L(0); PG8_BAR; PG8_MMA(0, 0, At, B0); PG8_MMA(0, 1, At, B1); PG8_BAR; PG8_SCHED;
;             PG8_LDA(At, 0, 1); PG8_STAGE(PG8_SB(0, 0), b2, voffB); PG8_STAGE(PG8_SB(0, 1), b2 + hstep, voffB); PG8_STAGE(PG8_SA(0, 0), a2, voffA);
;             PG8_WAIT_V(8); PG8_WAIT_L(0); PG8_BAR; PG8_MMA(1, 0, At, B0); PG8_MMA(1, 1, At, B1); PG8_BAR; PG8_SCHED;
.Lpeel_k248:
	s_add_u32 s6, s10, s94
	s_addc_u32 s7, s11, s95
	s_add_u32 s36, s6, 0xffffff80
	s_addc_u32 s37, s7, -1
	s_add_u32 s78, s12, s94
	s_addc_u32 s79, s13, s95
	s_cmp_eq_u32 s38, 28
	s_cselect_b32 s76, s90, s6
	s_cselect_b32 s77, s91, s7
	s_cselect_b32 s7, s93, s79
	s_cselect_b32 s6, s92, s78
	s_add_u32 s96, s76, 0x80
	s_addc_u32 s97, s77, 0
	s_add_u32 s78, s6, 0x80
	s_addc_u32 s79, s7, 0
	v_add_u32_e32 v128, s49, v163
	ds_read_b128 v[140:143], v128
	ds_read_b128 v[144:147], v128 offset:1024
	ds_read_b128 v[148:151], v128 offset:2048
	ds_read_b128 v[152:155], v128 offset:3072
	v_add_u32_e32 v128, s50, v163
	ds_read_b128 v[168:171], v128
	ds_read_b128 v[172:175], v128 offset:1024
	ds_read_b128 v[176:179], v128 offset:2048
	ds_read_b128 v[180:183], v128 offset:3072
	s_add_u32 s36, s36, 0x100000
	s_addc_u32 s37, s37, 0
	s_add_i32 m0, s42, 0xc000
	ds_read_b128 v[184:187], v165
	ds_read_b128 v[188:191], v165 offset:1024
	ds_read_b128 v[192:195], v165 offset:2048
	ds_read_b128 v[196:199], v165 offset:3072
	ds_read_b128 v[200:203], v165 offset:4096
	ds_read_b128 v[204:207], v165 offset:5120
	ds_read_b128 v[208:211], v165 offset:6144
	ds_read_b128 v[212:215], v165 offset:7168
	global_load_lds_dwordx4 v134, s[36:37]
	s_add_i32 m0, s42, 0xe000
	s_nop 0
	global_load_lds_dwordx4 v160, s[36:37]
	s_waitcnt vmcnt(8)
	s_waitcnt lgkmcnt(0)
	s_setprio 1
	s_barrier
	v_mfma_scale_f32_16x16x128_f8f6f4 v[124:127], v[140:147], v[184:191], 0, v166, v166 op_sel_hi:[0, 0, 0]
	v_mfma_scale_f32_16x16x128_f8f6f4 v[120:123], v[148:155], v[184:191], 0, v166, v166 op_sel_hi:[0, 0, 0]
	v_mfma_scale_f32_16x16x128_f8f6f4 v[116:119], v[140:147], v[192:199], 0, v166, v166 op_sel_hi:[0, 0, 0]
	v_mfma_scale_f32_16x16x128_f8f6f4 v[112:115], v[148:155], v[192:199], 0, v166, v166 op_sel_hi:[0, 0, 0]
	v_mfma_scale_f32_16x16x128_f8f6f4 v[108:111], v[140:147], v[200:207], 0, v166, v166 op_sel_hi:[0, 0, 0]
	v_mfma_scale_f32_16x16x128_f8f6f4 v[104:107], v[148:155], v[200:207], 0, v166, v166 op_sel_hi:[0, 0, 0]
	v_mfma_scale_f32_16x16x128_f8f6f4 v[100:103], v[140:147], v[208:215], 0, v166, v166 op_sel_hi:[0, 0, 0]
	v_mfma_scale_f32_16x16x128_f8f6f4 v[96:99], v[148:155], v[208:215], 0, v166, v166 op_sel_hi:[0, 0, 0]
	v_mfma_scale_f32_16x16x128_f8f6f4 v[156:159], v[168:175], v[184:191], 0, v166, v166 op_sel_hi:[0, 0, 0]
	v_mfma_scale_f32_16x16x128_f8f6f4 v[184:187], v[176:183], v[184:191], 0, v166, v166 op_sel_hi:[0, 0, 0]
	v_mfma_scale_f32_16x16x128_f8f6f4 v[188:191], v[168:175], v[192:199], 0, v166, v166 op_sel_hi:[0, 0, 0]
	v_mfma_scale_f32_16x16x128_f8f6f4 v[192:195], v[176:183], v[192:199], 0, v166, v166 op_sel_hi:[0, 0, 0]
	v_mfma_scale_f32_16x16x128_f8f6f4 v[196:199], v[168:175], v[200:207], 0, v166, v166 op_sel_hi:[0, 0, 0]
	v_mfma_scale_f32_16x16x128_f8f6f4 v[200:203], v[176:183], v[200:207], 0, v166, v166 op_sel_hi:[0, 0, 0]
	v_mfma_scale_f32_16x16x128_f8f6f4 v[204:207], v[168:175], v[208:215], 0, v166, v166 op_sel_hi:[0, 0, 0]
	v_mfma_scale_f32_16x16x128_f8f6f4 v[208:211], v[176:183], v[208:215], 0, v166, v166 op_sel_hi:[0, 0, 0]
	s_barrier
	s_setprio 0
	s_add_i32 s36, s49, s74
	s_mov_b32 m0, s36
	s_nop 1
	ds_read_b128 v[64:67], v165 offset:16384
	ds_read_b128 v[68:71], v165 offset:17408
	ds_read_b128 v[72:75], v165 offset:18432
	ds_read_b128 v[76:79], v165 offset:19456
	ds_read_b128 v[80:83], v165 offset:20480
	ds_read_b128 v[84:87], v165 offset:21504
	ds_read_b128 v[88:91], v165 offset:22528
	ds_read_b128 v[92:95], v165 offset:23552
	global_load_lds_dwordx4 v132, s[6:7]
	s_add_i32 m0, s36, 0x2000
	s_nop 0
	global_load_lds_dwordx4 v252, s[6:7]
	s_add_u32 s6, s6, 0x100000
	s_addc_u32 s7, s7, 0
	s_add_i32 s36, s50, s74
	s_mov_b32 m0, s36
	s_nop 0
	global_load_lds_dwordx4 v132, s[6:7]
	s_add_i32 m0, s36, 0x2000
	s_nop 0
	global_load_lds_dwordx4 v252, s[6:7]
	s_mov_b32 m0, s42
	s_nop 0
	global_load_lds_dwordx4 v134, s[76:77]
	s_mov_b32 m0, s43
	s_nop 0
	global_load_lds_dwordx4 v160, s[76:77]
	s_waitcnt vmcnt(8)
	s_waitcnt lgkmcnt(0)
	s_setprio 1
	s_barrier
	v_mfma_scale_f32_16x16x128_f8f6f4 v[60:63], v[140:147], v[64:71], 0, v166, v166 op_sel_hi:[0, 0, 0]
	v_mfma_scale_f32_16x16x128_f8f6f4 v[56:59], v[148:155], v[64:71], 0, v166, v166 op_sel_hi:[0, 0, 0]
	v_mfma_scale_f32_16x16x128_f8f6f4 v[52:55], v[140:147], v[72:79], 0, v166, v166 op_sel_hi:[0, 0, 0]
	v_mfma_scale_f32_16x16x128_f8f6f4 v[48:51], v[148:155], v[72:79], 0, v166, v166 op_sel_hi:[0, 0, 0]
	v_mfma_scale_f32_16x16x128_f8f6f4 v[212:215], v[140:147], v[80:87], 0, v166, v166 op_sel_hi:[0, 0, 0]
	v_mfma_scale_f32_16x16x128_f8f6f4 v[216:219], v[148:155], v[80:87], 0, v166, v166 op_sel_hi:[0, 0, 0]
	v_mfma_scale_f32_16x16x128_f8f6f4 v[220:223], v[140:147], v[88:95], 0, v166, v166 op_sel_hi:[0, 0, 0]
	v_mfma_scale_f32_16x16x128_f8f6f4 v[224:227], v[148:155], v[88:95], 0, v166, v166 op_sel_hi:[0, 0, 0]
	v_mfma_scale_f32_16x16x128_f8f6f4 v[228:231], v[168:175], v[64:71], 0, v166, v166 op_sel_hi:[0, 0, 0]
	v_mfma_scale_f32_16x16x128_f8f6f4 v[236:239], v[176:183], v[64:71], 0, v166, v166 op_sel_hi:[0, 0, 0]
	v_mfma_scale_f32_16x16x128_f8f6f4 v[244:247], v[168:175], v[72:79], 0, v166, v166 op_sel_hi:[0, 0, 0]
	v_mfma_scale_f32_16x16x128_f8f6f4 v[248:251], v[176:183], v[72:79], 0, v166, v166 op_sel_hi:[0, 0, 0]
	v_mfma_scale_f32_16x16x128_f8f6f4 v[232:235], v[168:175], v[80:87], 0, v166, v166 op_sel_hi:[0, 0, 0]
	v_mfma_scale_f32_16x16x128_f8f6f4 v[240:243], v[176:183], v[80:87], 0, v166, v166 op_sel_hi:[0, 0, 0]
	v_mfma_scale_f32_16x16x128_f8f6f4 v[136:139], v[168:175], v[88:95], 0, v166, v166 op_sel_hi:[0, 0, 0]
	v_mfma_scale_f32_16x16x128_f8f6f4 v[128:131], v[176:183], v[88:95], 0, v166, v166 op_sel_hi:[0, 0, 0]
	s_barrier
	s_branch .Lmid_k248
; #define PG8_STAGE(bufoff, gbase, voff) do { _Pragma("unroll") for (int _i = 0; _i < 2; ++_i) \
;         __builtin_amdgcn_global_load_lds((const unsigned*)((const char*)(gbase) + (voff)[_i]), (PG8_LAS unsigned*)(lds + (bufoff) + ldsw + _i * 8192), 16, 0, 0); } while (0)
; #define PG8_LDA(dst, b, h) do { _Pragma("unroll") for (int m = 0; m < 4; ++m) _Pragma("unroll") for (int k = 0; k < 2; ++k) dst[m][k] = *(const PG8_LAS bf16x8*)(lds + PG8_SA(b, h) + aoff + m * 2048 + k * 1024); } while (0)
; #define PG8_LDB(dst, b, h) do { _Pragma("unroll") for (int n = 0; n < 2; ++n) _Pragma("unroll") for (int k = 0; k < 2; ++k) dst[n][k] = *(const PG8_LAS bf16x8*)(lds + PG8_SB(b, h) + boff + n * 2048 + k * 1024); } while (0)
; #define PG8_WAIT_V(n) asm volatile("s_waitcnt vmcnt(" #n ")" ::: "memory")
; #define PG8_WAIT_L(n) asm volatile("s_waitcnt lgkmcnt(" #n ")" ::: "memory")
; #define PG8_BAR __builtin_amdgcn_s_barrier()
; template <class Epi, class Sched, bool ALIGN_EPI = false, bool SP2 = false, bool F8 = false>
; __device__ __forceinline__ void gemm_phase(PG8_LAS unsigned char* lds, const int K, const Sched& S, const Epi& E, const int wave) {
;     ...
;             const bool last = (t == nt - 2);
;             const char* a1 = cA + (size_t)(t + 1) * kstep;
;             const char* a2 = last ? nA : cA + (size_t)(t + 2) * kstep; const char* b2 = last ? nB : cB + (size_t)(t + 2) * kstep;
;             const char* a3 = a2 + kstep; const char* b3 = b2 + kstep;
;             asm volatile("" : "+s"(a1), "+s"(a2), "+s"(b2), "+s"(a3), "+s"(b3));
;             if (last && has_next) S.a_ready(nxt);
;             if constexpr (Epi::KHOOK) { if (cur.prob == 2 ? (t == 16) : (t == 32 || t == 48)) { if (wr == 0) PG8_BAR;
;                 E.khook(acc, cur, (cur.prob == 2 || t == 48) ? 1 : 0, wr, wc, fr, fq); if (wr == 1) PG8_BAR; } }
;             if constexpr (SP2) {
;             PG8_LDB(B0, 0, 0); PG8_LDB(B1, 0, 1); PG8_SCHED; PG8_LDA(At, 0, 0); PG8_STAGE(PG8_SA(1, 1), a1 + hstep, voffA);
;             PG8_WAIT_V(8); PG8_WAIT_L(0); PG8_BAR; PG8_MMA(0, 0, At, B0); PG8_MMA(0, 1, At, B1); PG8_BAR; PG8_SCHED;
;             PG8_LDA(At, 0, 1); PG8_STAGE(PG8_SB(0, 0), b2, voffB); PG8_STAGE(PG8_SB(0, 1), b2 + hstep, voffB); PG8_STAGE(PG8_SA(0, 0), a2, voffA);
;             PG8_WAIT_V(8); PG8_WAIT_L(0); PG8_BAR; PG8_MMA(1, 0, At, B0); PG8_MMA(1, 1, At, B1); PG8_BAR; PG8_SCHED;
.LBB0_248:
	s_add_u32 s6, s10, s94
	s_addc_u32 s7, s11, s95
	s_add_u32 s36, s6, 0xffffff80
	s_addc_u32 s37, s7, -1
	s_add_u32 s78, s12, s94
	s_addc_u32 s79, s13, s95
	s_cmp_eq_u32 s38, 28
	s_cselect_b32 s76, s90, s6
	s_cselect_b32 s77, s91, s7
	s_cselect_b32 s7, s93, s79
	s_cselect_b32 s6, s92, s78
	s_add_u32 s96, s76, 0x80
	s_addc_u32 s97, s77, 0
	s_add_u32 s78, s6, 0x80
	s_addc_u32 s79, s7, 0
	v_add_u32_e32 v128, s49, v163
	ds_read_b128 v[140:143], v128
	ds_read_b128 v[144:147], v128 offset:1024
	ds_read_b128 v[148:151], v128 offset:2048
	ds_read_b128 v[152:155], v128 offset:3072
	v_add_u32_e32 v128, s50, v163
	ds_read_b128 v[168:171], v128
	ds_read_b128 v[172:175], v128 offset:1024
	ds_read_b128 v[176:179], v128 offset:2048
	ds_read_b128 v[180:183], v128 offset:3072
	s_add_u32 s36, s36, 0x100000
	s_addc_u32 s37, s37, 0
	s_add_i32 m0, s42, 0xc000
	ds_read_b128 v[184:187], v165
	ds_read_b128 v[188:191], v165 offset:1024
	ds_read_b128 v[192:195], v165 offset:2048
	ds_read_b128 v[196:199], v165 offset:3072
	ds_read_b128 v[200:203], v165 offset:4096
	ds_read_b128 v[204:207], v165 offset:5120
	ds_read_b128 v[208:211], v165 offset:6144
	ds_read_b128 v[212:215], v165 offset:7168
	global_load_lds_dwordx4 v134, s[36:37]
	s_add_i32 m0, s42, 0xe000
	s_nop 0
	global_load_lds_dwordx4 v160, s[36:37]
	s_waitcnt vmcnt(8)
	s_waitcnt lgkmcnt(0)
	s_setprio 1
	s_barrier
	v_mfma_scale_f32_16x16x128_f8f6f4 v[124:127], v[140:147], v[184:191], v[124:127], v166, v166 op_sel_hi:[0,0,0]
	v_mfma_scale_f32_16x16x128_f8f6f4 v[120:123], v[148:155], v[184:191], v[120:123], v166, v166 op_sel_hi:[0,0,0]
	v_mfma_scale_f32_16x16x128_f8f6f4 v[116:119], v[140:147], v[192:199], v[116:119], v166, v166 op_sel_hi:[0,0,0]
	v_mfma_scale_f32_16x16x128_f8f6f4 v[112:115], v[148:155], v[192:199], v[112:115], v166, v166 op_sel_hi:[0,0,0]
	v_mfma_scale_f32_16x16x128_f8f6f4 v[108:111], v[140:147], v[200:207], v[108:111], v166, v166 op_sel_hi:[0,0,0]
	v_mfma_scale_f32_16x16x128_f8f6f4 v[104:107], v[148:155], v[200:207], v[104:107], v166, v166 op_sel_hi:[0,0,0]
	v_mfma_scale_f32_16x16x128_f8f6f4 v[100:103], v[140:147], v[208:215], v[100:103], v166, v166 op_sel_hi:[0,0,0]
	v_mfma_scale_f32_16x16x128_f8f6f4 v[96:99], v[148:155], v[208:215], v[96:99], v166, v166 op_sel_hi:[0,0,0]
	v_mfma_scale_f32_16x16x128_f8f6f4 v[156:159], v[168:175], v[184:191], v[92:95], v166, v166 op_sel_hi:[0,0,0]
	v_mfma_scale_f32_16x16x128_f8f6f4 v[184:187], v[176:183], v[184:191], v[88:91], v166, v166 op_sel_hi:[0,0,0]
	v_mfma_scale_f32_16x16x128_f8f6f4 v[188:191], v[168:175], v[192:199], v[84:87], v166, v166 op_sel_hi:[0,0,0]
	v_mfma_scale_f32_16x16x128_f8f6f4 v[192:195], v[176:183], v[192:199], v[80:83], v166, v166 op_sel_hi:[0,0,0]
	v_mfma_scale_f32_16x16x128_f8f6f4 v[196:199], v[168:175], v[200:207], v[76:79], v166, v166 op_sel_hi:[0,0,0]
	v_mfma_scale_f32_16x16x128_f8f6f4 v[200:203], v[176:183], v[200:207], v[72:75], v166, v166 op_sel_hi:[0,0,0]
	v_mfma_scale_f32_16x16x128_f8f6f4 v[204:207], v[168:175], v[208:215], v[68:71], v166, v166 op_sel_hi:[0,0,0]
	v_mfma_scale_f32_16x16x128_f8f6f4 v[208:211], v[176:183], v[208:215], v[64:67], v166, v166 op_sel_hi:[0,0,0]
	s_barrier
	s_setprio 0
	s_add_i32 s36, s49, s74
	s_mov_b32 m0, s36
	s_nop 1
	ds_read_b128 v[64:67], v165 offset:16384
	ds_read_b128 v[68:71], v165 offset:17408
	ds_read_b128 v[72:75], v165 offset:18432
	ds_read_b128 v[76:79], v165 offset:19456
	ds_read_b128 v[80:83], v165 offset:20480
	ds_read_b128 v[84:87], v165 offset:21504
	ds_read_b128 v[88:91], v165 offset:22528
	ds_read_b128 v[92:95], v165 offset:23552
	global_load_lds_dwordx4 v132, s[6:7]
	s_add_i32 m0, s36, 0x2000
	s_nop 0
	global_load_lds_dwordx4 v252, s[6:7]
	s_add_u32 s6, s6, 0x100000
	s_addc_u32 s7, s7, 0
	s_add_i32 s36, s50, s74
	s_mov_b32 m0, s36
	s_nop 0
	global_load_lds_dwordx4 v132, s[6:7]
	s_add_i32 m0, s36, 0x2000
	s_nop 0
	global_load_lds_dwordx4 v252, s[6:7]
	s_mov_b32 m0, s42
	s_nop 0
	global_load_lds_dwordx4 v134, s[76:77]
	s_mov_b32 m0, s43
	s_nop 0
	global_load_lds_dwordx4 v160, s[76:77]
	s_waitcnt vmcnt(8)
	s_waitcnt lgkmcnt(0)
	s_setprio 1
	s_barrier
	v_mfma_scale_f32_16x16x128_f8f6f4 v[60:63], v[140:147], v[64:71], v[60:63], v166, v166 op_sel_hi:[0,0,0]
	v_mfma_scale_f32_16x16x128_f8f6f4 v[56:59], v[148:155], v[64:71], v[56:59], v166, v166 op_sel_hi:[0,0,0]
	v_mfma_scale_f32_16x16x128_f8f6f4 v[52:55], v[140:147], v[72:79], v[52:55], v166, v166 op_sel_hi:[0,0,0]
	v_mfma_scale_f32_16x16x128_f8f6f4 v[48:51], v[148:155], v[72:79], v[48:51], v166, v166 op_sel_hi:[0,0,0]
	v_mfma_scale_f32_16x16x128_f8f6f4 v[212:215], v[140:147], v[80:87], v[44:47], v166, v166 op_sel_hi:[0,0,0]
	v_mfma_scale_f32_16x16x128_f8f6f4 v[216:219], v[148:155], v[80:87], v[40:43], v166, v166 op_sel_hi:[0,0,0]
	v_mfma_scale_f32_16x16x128_f8f6f4 v[220:223], v[140:147], v[88:95], v[36:39], v166, v166 op_sel_hi:[0,0,0]
	v_mfma_scale_f32_16x16x128_f8f6f4 v[224:227], v[148:155], v[88:95], v[32:35], v166, v166 op_sel_hi:[0,0,0]
	v_mfma_scale_f32_16x16x128_f8f6f4 v[228:231], v[168:175], v[64:71], v[28:31], v166, v166 op_sel_hi:[0,0,0]
	v_mfma_scale_f32_16x16x128_f8f6f4 v[236:239], v[176:183], v[64:71], v[24:27], v166, v166 op_sel_hi:[0,0,0]
	v_mfma_scale_f32_16x16x128_f8f6f4 v[244:247], v[168:175], v[72:79], v[20:23], v166, v166 op_sel_hi:[0,0,0]
	v_mfma_scale_f32_16x16x128_f8f6f4 v[248:251], v[176:183], v[72:79], v[16:19], v166, v166 op_sel_hi:[0,0,0]
	v_mfma_scale_f32_16x16x128_f8f6f4 v[232:235], v[168:175], v[80:87], v[12:15], v166, v166 op_sel_hi:[0,0,0]
	v_mfma_scale_f32_16x16x128_f8f6f4 v[240:243], v[176:183], v[80:87], v[8:11], v166, v166 op_sel_hi:[0,0,0]
	v_mfma_scale_f32_16x16x128_f8f6f4 v[136:139], v[168:175], v[88:95], v[4:7], v166, v166 op_sel_hi:[0,0,0]
	v_mfma_scale_f32_16x16x128_f8f6f4 v[128:131], v[176:183], v[88:95], v[0:3], v166, v166 op_sel_hi:[0,0,0]
	s_barrier
; #define PG8_STAGE(bufoff, gbase, voff) do { _Pragma("unroll") for (int _i = 0; _i < 2; ++_i) \
;         __builtin_amdgcn_global_load_lds((const unsigned*)((const char*)(gbase) + (voff)[_i]), (PG8_LAS unsigned*)(lds + (bufoff) + ldsw + _i * 8192), 16, 0, 0); } while (0)
; #define PG8_LDA(dst, b, h) do { _Pragma("unroll") for (int m = 0; m < 4; ++m) _Pragma("unroll") for (int k = 0; k < 2; ++k) dst[m][k] = *(const PG8_LAS bf16x8*)(lds + PG8_SA(b, h) + aoff + m * 2048 + k * 1024); } while (0)
; #define PG8_LDB(dst, b, h) do { _Pragma("unroll") for (int n = 0; n < 2; ++n) _Pragma("unroll") for (int k = 0; k < 2; ++k) dst[n][k] = *(const PG8_LAS bf16x8*)(lds + PG8_SB(b, h) + boff + n * 2048 + k * 1024); } while (0)
; #define PG8_WAIT_V(n) asm volatile("s_waitcnt vmcnt(" #n ")" ::: "memory")
; #define PG8_WAIT_L(n) asm volatile("s_waitcnt lgkmcnt(" #n ")" ::: "memory")
; #define PG8_BAR __builtin_amdgcn_s_barrier()
; #define PG8_SCHED __builtin_amdgcn_sched_barrier(0)
; template <class Epi, class Sched, bool ALIGN_EPI = false, bool SP2 = false, bool F8 = false>
; __device__ __forceinline__ void gemm_phase(PG8_LAS unsigned char* lds, const int K, const Sched& S, const Epi& E, const int wave) {
;     ...
;             PG8_LDB(B0, 1, 0); PG8_LDB(B1, 1, 1); PG8_SCHED; PG8_LDA(At, 1, 0); PG8_STAGE(PG8_SA(0, 1), a2 + hstep, voffA);
;             PG8_WAIT_V(8); PG8_WAIT_L(0); PG8_BAR; PG8_MMA(0, 0, At, B0); PG8_MMA(0, 1, At, B1); PG8_BAR; PG8_SCHED;
;             PG8_LDA(At, 1, 1); PG8_STAGE(PG8_SB(1, 0), b3, voffB); PG8_STAGE(PG8_SB(1, 1), b3 + hstep, voffB); PG8_STAGE(PG8_SA(1, 0), a3, voffA);
;             PG8_WAIT_V(8); PG8_WAIT_L(0); PG8_BAR; PG8_MMA(1, 0, At, B0); PG8_MMA(1, 1, At, B1); PG8_BAR; PG8_SCHED;
.Lmid_k248:
	s_setprio 0
	s_add_i32 s36, 0, 0x18000
	s_add_i32 s37, 0, 0x1c000
	v_add_u32_e32 v12, s36, v163
	v_add_u32_e32 v16, s37, v163
	s_nop 0
	ds_read_b128 v[0:3], v12
	ds_read_b128 v[4:7], v12 offset:1024
	ds_read_b128 v[8:11], v12 offset:2048
	ds_read_b128 v[12:15], v12 offset:3072
	ds_read_b128 v[140:143], v16
	ds_read_b128 v[144:147], v16 offset:1024
	ds_read_b128 v[148:151], v16 offset:2048
	ds_read_b128 v[152:155], v16 offset:3072
	s_add_u32 s6, s76, 0x100000
	s_addc_u32 s7, s77, 0
	s_mov_b32 m0, s44
	ds_read_b128 v[16:19], v165 offset:32768
	ds_read_b128 v[20:23], v165 offset:33792
	ds_read_b128 v[24:27], v165 offset:34816
	ds_read_b128 v[28:31], v165 offset:35840
	ds_read_b128 v[32:35], v165 offset:36864
	ds_read_b128 v[36:39], v165 offset:37888
	ds_read_b128 v[40:43], v165 offset:38912
	ds_read_b128 v[44:47], v165 offset:39936
	global_load_lds_dwordx4 v134, s[6:7]
	s_mov_b32 m0, s45
	s_nop 0
	global_load_lds_dwordx4 v160, s[6:7]
	s_waitcnt vmcnt(8)
	s_waitcnt lgkmcnt(0)
	s_setprio 1
	s_barrier
	v_mfma_scale_f32_16x16x128_f8f6f4 v[124:127], v[0:7], v[16:23], v[124:127], v166, v166 op_sel_hi:[0,0,0]
	v_mfma_scale_f32_16x16x128_f8f6f4 v[120:123], v[8:15], v[16:23], v[120:123], v166, v166 op_sel_hi:[0,0,0]
	v_mfma_scale_f32_16x16x128_f8f6f4 v[116:119], v[0:7], v[24:31], v[116:119], v166, v166 op_sel_hi:[0,0,0]
	v_mfma_scale_f32_16x16x128_f8f6f4 v[112:115], v[8:15], v[24:31], v[112:115], v166, v166 op_sel_hi:[0,0,0]
	v_mfma_scale_f32_16x16x128_f8f6f4 v[108:111], v[0:7], v[32:39], v[108:111], v166, v166 op_sel_hi:[0,0,0]
	v_mfma_scale_f32_16x16x128_f8f6f4 v[104:107], v[8:15], v[32:39], v[104:107], v166, v166 op_sel_hi:[0,0,0]
	v_mfma_scale_f32_16x16x128_f8f6f4 v[100:103], v[0:7], v[40:47], v[100:103], v166, v166 op_sel_hi:[0,0,0]
	v_mfma_scale_f32_16x16x128_f8f6f4 v[96:99], v[8:15], v[40:47], v[96:99], v166, v166 op_sel_hi:[0,0,0]
	v_mfma_scale_f32_16x16x128_f8f6f4 v[92:95], v[140:147], v[16:23], v[156:159], v166, v166 op_sel_hi:[0,0,0]
	v_mfma_scale_f32_16x16x128_f8f6f4 v[88:91], v[148:155], v[16:23], v[184:187], v166, v166 op_sel_hi:[0,0,0]
	v_mfma_scale_f32_16x16x128_f8f6f4 v[84:87], v[140:147], v[24:31], v[188:191], v166, v166 op_sel_hi:[0,0,0]
	v_mfma_scale_f32_16x16x128_f8f6f4 v[80:83], v[148:155], v[24:31], v[192:195], v166, v166 op_sel_hi:[0,0,0]
	v_mfma_scale_f32_16x16x128_f8f6f4 v[76:79], v[140:147], v[32:39], v[196:199], v166, v166 op_sel_hi:[0,0,0]
	v_mfma_scale_f32_16x16x128_f8f6f4 v[72:75], v[148:155], v[32:39], v[200:203], v166, v166 op_sel_hi:[0,0,0]
	v_mfma_scale_f32_16x16x128_f8f6f4 v[68:71], v[140:147], v[40:47], v[204:207], v166, v166 op_sel_hi:[0,0,0]
	v_mfma_scale_f32_16x16x128_f8f6f4 v[64:67], v[148:155], v[40:47], v[208:211], v166, v166 op_sel_hi:[0,0,0]
	s_barrier
	s_setprio 0
	s_add_i32 s6, s36, s74
	s_mov_b32 m0, s6
	ds_read_b128 v[16:19], v165 offset:49152
	ds_read_b128 v[20:23], v165 offset:50176
	ds_read_b128 v[168:171], v165 offset:51200
	ds_read_b128 v[172:175], v165 offset:52224
	ds_read_b128 v[176:179], v165 offset:53248
	ds_read_b128 v[180:183], v165 offset:54272
	ds_read_b128 v[184:187], v165 offset:55296
	ds_read_b128 v[188:191], v165 offset:56320
	global_load_lds_dwordx4 v132, s[78:79]
	s_add_i32 m0, s6, 0x2000
	s_add_u32 s6, s78, 0x100000
	s_addc_u32 s7, s79, 0
	s_add_i32 s36, s37, s74
	global_load_lds_dwordx4 v252, s[78:79]
	s_mov_b32 m0, s36
	s_nop 0
	global_load_lds_dwordx4 v132, s[6:7]
	s_add_i32 m0, s36, 0x2000
	s_nop 0
	global_load_lds_dwordx4 v252, s[6:7]
	s_mov_b32 m0, s46
	s_nop 0
	global_load_lds_dwordx4 v134, s[96:97]
	s_mov_b32 m0, s47
	s_nop 0
	global_load_lds_dwordx4 v160, s[96:97]
	s_waitcnt vmcnt(8)
	s_waitcnt lgkmcnt(0)
	s_setprio 1
	s_barrier
	v_mfma_scale_f32_16x16x128_f8f6f4 v[60:63], v[0:7], v[16:23], v[60:63], v166, v166 op_sel_hi:[0,0,0]
	v_mfma_scale_f32_16x16x128_f8f6f4 v[56:59], v[8:15], v[16:23], v[56:59], v166, v166 op_sel_hi:[0,0,0]
	v_mfma_scale_f32_16x16x128_f8f6f4 v[52:55], v[0:7], v[168:175], v[52:55], v166, v166 op_sel_hi:[0,0,0]
	v_mfma_scale_f32_16x16x128_f8f6f4 v[48:51], v[8:15], v[168:175], v[48:51], v166, v166 op_sel_hi:[0,0,0]
	v_mfma_scale_f32_16x16x128_f8f6f4 v[44:47], v[0:7], v[176:183], v[212:215], v166, v166 op_sel_hi:[0,0,0]
	v_mfma_scale_f32_16x16x128_f8f6f4 v[40:43], v[8:15], v[176:183], v[216:219], v166, v166 op_sel_hi:[0,0,0]
	v_mfma_scale_f32_16x16x128_f8f6f4 v[36:39], v[0:7], v[184:191], v[220:223], v166, v166 op_sel_hi:[0,0,0]
	v_mfma_scale_f32_16x16x128_f8f6f4 v[32:35], v[8:15], v[184:191], v[224:227], v166, v166 op_sel_hi:[0,0,0]
	v_mfma_scale_f32_16x16x128_f8f6f4 v[28:31], v[140:147], v[16:23], v[228:231], v166, v166 op_sel_hi:[0,0,0]
	v_mfma_scale_f32_16x16x128_f8f6f4 v[24:27], v[148:155], v[16:23], v[236:239], v166, v166 op_sel_hi:[0,0,0]
	v_mfma_scale_f32_16x16x128_f8f6f4 v[20:23], v[140:147], v[168:175], v[244:247], v166, v166 op_sel_hi:[0,0,0]
	v_mfma_scale_f32_16x16x128_f8f6f4 v[16:19], v[148:155], v[168:175], v[248:251], v166, v166 op_sel_hi:[0,0,0]
	v_mfma_scale_f32_16x16x128_f8f6f4 v[12:15], v[140:147], v[176:183], v[232:235], v166, v166 op_sel_hi:[0,0,0]
	v_mfma_scale_f32_16x16x128_f8f6f4 v[8:11], v[148:155], v[176:183], v[240:243], v166, v166 op_sel_hi:[0,0,0]
	v_mfma_scale_f32_16x16x128_f8f6f4 v[4:7], v[140:147], v[184:191], v[136:139], v166, v166 op_sel_hi:[0,0,0]
	v_mfma_scale_f32_16x16x128_f8f6f4 v[0:3], v[148:155], v[184:191], v[128:131], v166, v166 op_sel_hi:[0,0,0]
	s_barrier
	s_setprio 0
	s_add_i32 s38, s38, 2
	s_add_u32 s94, s94, 0x100
	s_addc_u32 s95, s95, 0
	s_cmp_gt_u32 s38, 29
	s_cbranch_scc0 .LBB0_248
	s_and_b64 vcc, exec, s[60:61]
	s_cbranch_vccz .LBB0_251
	s_barrier

; #define PG8_STAGE(bufoff, gbase, voff) do { _Pragma("unroll") for (int _i = 0; _i < 2; ++_i) \
;         __builtin_amdgcn_global_load_lds((const unsigned*)((const char*)(gbase) + (voff)[_i]), (PG8_LAS unsigned*)(lds + (bufoff) + ldsw + _i * 8192), 16, 0, 0); } while (0)
; #define PG8_LDA(dst, b, h) do { _Pragma("unroll") for (int m = 0; m < 4; ++m) _Pragma("unroll") for (int k = 0; k < 2; ++k) dst[m][k] = *(const PG8_LAS bf16x8*)(lds + PG8_SA(b, h) + aoff + m * 2048 + k * 1024); } while (0)
; #define PG8_LDB(dst, b, h) do { _Pragma("unroll") for (int n = 0; n < 2; ++n) _Pragma("unroll") for (int k = 0; k < 2; ++k) dst[n][k] = *(const PG8_LAS bf16x8*)(lds + PG8_SB(b, h) + boff + n * 2048 + k * 1024); } while (0)
; #define PG8_WAIT_V(n) asm volatile("s_waitcnt vmcnt(" #n ")" ::: "memory")
; #define PG8_WAIT_L(n) asm volatile("s_waitcnt lgkmcnt(" #n ")" ::: "memory")
; #define PG8_BAR __builtin_amdgcn_s_barrier()
; template <class Epi, class Sched, bool ALIGN_EPI = false, bool SP2 = false, bool F8 = false>
; __device__ __forceinline__ void gemm_phase(PG8_LAS unsigned char* lds, const int K, const Sched& S, const Epi& E, const int wave) {
;     ...
;             const bool last = (t == nt - 2);
;             const char* a1 = cA + (size_t)(t + 1) * kstep;
;             const char* a2 = last ? nA : cA + (size_t)(t + 2) * kstep; const char* b2 = last ? nB : cB + (size_t)(t + 2) * kstep;
;             const char* a3 = a2 + kstep; const char* b3 = b2 + kstep;
;             asm volatile("" : "+s"(a1), "+s"(a2), "+s"(b2), "+s"(a3), "+s"(b3));
;             if (last && has_next) S.a_ready(nxt);
;             if constexpr (Epi::KHOOK) { if (cur.prob == 2 ? (t == 16) : (t == 32 || t == 48)) { if (wr == 0) PG8_BAR;
;                 E.khook(acc, cur, (cur.prob == 2 || t == 48) ? 1 : 0, wr, wc, fr, fq); if (wr == 1) PG8_BAR; } }
;             if constexpr (SP2) {
;             PG8_LDB(B0, 0, 0); PG8_LDB(B1, 0, 1); PG8_SCHED; PG8_LDA(At, 0, 0); PG8_STAGE(PG8_SA(1, 1), a1 + hstep, voffA);
;             PG8_WAIT_V(8); PG8_WAIT_L(0); PG8_BAR; PG8_MMA(0, 0, At, B0); PG8_MMA(0, 1, At, B1); PG8_BAR; PG8_SCHED;
;             PG8_LDA(At, 0, 1); PG8_STAGE(PG8_SB(0, 0), b2, voffB); PG8_STAGE(PG8_SB(0, 1), b2 + hstep, voffB); PG8_STAGE(PG8_SA(0, 0), a2, voffA);
;             PG8_WAIT_V(8); PG8_WAIT_L(0); PG8_BAR; PG8_MMA(1, 0, At, B0); PG8_MMA(1, 1, At, B1); PG8_BAR; PG8_SCHED;
.Lpeel_k966:
	s_add_i32 s90, s8, 2
	s_cmp_eq_u32 s85, s8
	s_cselect_b32 s42, s31, s86
	s_cselect_b32 s43, s25, s87
	s_cselect_b32 s57, s83, s89
	s_cselect_b32 s56, s84, s88
	s_add_u32 s8, s42, 0x80
	s_addc_u32 s9, s43, 0
	s_add_u32 s40, s56, 0x80
	s_addc_u32 s41, s57, 0
	s_mov_b64 s[92:93], s[6:7]
	v_add_u32_e32 v1, s77, v168
	ds_read_b128 v[132:135], v1
	ds_read_b128 v[136:139], v1 offset:1024
	ds_read_b128 v[156:159], v1 offset:2048
	ds_read_b128 v[160:163], v1 offset:3072
	v_add_u32_e32 v1, s78, v168
	ds_read_b128 v[172:175], v1
	ds_read_b128 v[176:179], v1 offset:1024
	ds_read_b128 v[180:183], v1 offset:2048
	ds_read_b128 v[184:187], v1 offset:3072
	s_add_u32 s92, s92, 0x100000
	s_addc_u32 s93, s93, 0
	s_add_i32 m0, s64, 0xc000
	ds_read_b128 v[188:191], v170
	ds_read_b128 v[192:195], v170 offset:1024
	ds_read_b128 v[196:199], v170 offset:2048
	ds_read_b128 v[200:203], v170 offset:3072
	ds_read_b128 v[204:207], v170 offset:4096
	ds_read_b128 v[208:211], v170 offset:5120
	ds_read_b128 v[212:215], v170 offset:6144
	ds_read_b128 v[216:219], v170 offset:7168
	global_load_lds_dwordx4 v140, s[92:93]
	s_add_i32 m0, s64, 0xe000
	s_nop 0
	global_load_lds_dwordx4 v144, s[92:93]
	s_waitcnt vmcnt(8)
	s_waitcnt lgkmcnt(0)
	s_setprio 1
	s_barrier
	v_mfma_f32_16x16x32_bf16 v[128:131], v[132:135], v[188:191], 0
	v_mfma_f32_16x16x32_bf16 v[124:127], v[156:159], v[188:191], 0
	v_mfma_f32_16x16x32_bf16 v[120:123], v[132:135], v[196:199], 0
	v_mfma_f32_16x16x32_bf16 v[116:119], v[156:159], v[196:199], 0
	v_mfma_f32_16x16x32_bf16 v[112:115], v[132:135], v[204:207], 0
	v_mfma_f32_16x16x32_bf16 v[108:111], v[156:159], v[204:207], 0
	v_mfma_f32_16x16x32_bf16 v[104:107], v[132:135], v[212:215], 0
	v_mfma_f32_16x16x32_bf16 v[100:103], v[156:159], v[212:215], 0
	v_mfma_f32_16x16x32_bf16 v[128:131], v[136:139], v[192:195], v[128:131]
	v_mfma_f32_16x16x32_bf16 v[124:127], v[160:163], v[192:195], v[124:127]
	v_mfma_f32_16x16x32_bf16 v[120:123], v[136:139], v[200:203], v[120:123]
	v_mfma_f32_16x16x32_bf16 v[116:119], v[160:163], v[200:203], v[116:119]
	v_mfma_f32_16x16x32_bf16 v[112:115], v[136:139], v[208:211], v[112:115]
	v_mfma_f32_16x16x32_bf16 v[108:111], v[160:163], v[208:211], v[108:111]
	v_mfma_f32_16x16x32_bf16 v[104:107], v[136:139], v[216:219], v[104:107]
	v_mfma_f32_16x16x32_bf16 v[100:103], v[160:163], v[216:219], v[100:103]
	v_mfma_f32_16x16x32_bf16 v[96:99], v[172:175], v[188:191], 0
	v_mfma_f32_16x16x32_bf16 v[92:95], v[180:183], v[188:191], 0
	v_mfma_f32_16x16x32_bf16 v[88:91], v[172:175], v[196:199], 0
	v_mfma_f32_16x16x32_bf16 v[84:87], v[180:183], v[196:199], 0
	v_mfma_f32_16x16x32_bf16 v[80:83], v[172:175], v[204:207], 0
	v_mfma_f32_16x16x32_bf16 v[76:79], v[180:183], v[204:207], 0
	v_mfma_f32_16x16x32_bf16 v[72:75], v[172:175], v[212:215], 0
	v_mfma_f32_16x16x32_bf16 v[68:71], v[180:183], v[212:215], 0
	v_mfma_f32_16x16x32_bf16 v[96:99], v[176:179], v[192:195], v[96:99]
	v_mfma_f32_16x16x32_bf16 v[92:95], v[184:187], v[192:195], v[92:95]
	v_mfma_f32_16x16x32_bf16 v[88:91], v[176:179], v[200:203], v[88:91]
	v_mfma_f32_16x16x32_bf16 v[84:87], v[184:187], v[200:203], v[84:87]
	v_mfma_f32_16x16x32_bf16 v[80:83], v[176:179], v[208:211], v[80:83]
	v_mfma_f32_16x16x32_bf16 v[76:79], v[184:187], v[208:211], v[76:79]
	v_mfma_f32_16x16x32_bf16 v[72:75], v[176:179], v[216:219], v[72:75]
	v_mfma_f32_16x16x32_bf16 v[68:71], v[184:187], v[216:219], v[68:71]
	s_barrier
	s_setprio 0
	s_add_i32 s91, s77, s63
	s_mov_b32 m0, s91
	ds_read_b128 v[188:191], v170 offset:16384
	ds_read_b128 v[192:195], v170 offset:17408
	ds_read_b128 v[196:199], v170 offset:18432
	ds_read_b128 v[200:203], v170 offset:19456
	ds_read_b128 v[204:207], v170 offset:20480
	ds_read_b128 v[208:211], v170 offset:21504
	ds_read_b128 v[212:215], v170 offset:22528
	ds_read_b128 v[216:219], v170 offset:23552
	global_load_lds_dwordx4 v142, s[56:57]
	s_add_i32 m0, s91, 0x2000
	s_nop 0
	global_load_lds_dwordx4 v146, s[56:57]
	s_add_u32 s56, s56, 0x100000
	s_addc_u32 s57, s57, 0
	s_add_i32 s91, s78, s63
	s_mov_b32 m0, s91
	s_nop 0
	global_load_lds_dwordx4 v142, s[56:57]
	s_add_i32 m0, s91, 0x2000
	s_nop 0
	global_load_lds_dwordx4 v146, s[56:57]
	s_mov_b32 m0, s64
	s_nop 0
	global_load_lds_dwordx4 v140, s[42:43]
	s_mov_b32 m0, s65
	s_nop 0
	global_load_lds_dwordx4 v144, s[42:43]
	s_waitcnt vmcnt(8)
	s_waitcnt lgkmcnt(0)
	s_setprio 1
	s_barrier
	v_mfma_f32_16x16x32_bf16 v[64:67], v[132:135], v[188:191], 0
	v_mfma_f32_16x16x32_bf16 v[60:63], v[156:159], v[188:191], 0
	v_mfma_f32_16x16x32_bf16 v[56:59], v[132:135], v[196:199], 0
	v_mfma_f32_16x16x32_bf16 v[52:55], v[156:159], v[196:199], 0
	v_mfma_f32_16x16x32_bf16 v[48:51], v[132:135], v[204:207], 0
	v_mfma_f32_16x16x32_bf16 v[44:47], v[156:159], v[204:207], 0
	v_mfma_f32_16x16x32_bf16 v[40:43], v[132:135], v[212:215], 0
	v_mfma_f32_16x16x32_bf16 v[36:39], v[156:159], v[212:215], 0
	v_mfma_f32_16x16x32_bf16 v[64:67], v[136:139], v[192:195], v[64:67]
	v_mfma_f32_16x16x32_bf16 v[60:63], v[160:163], v[192:195], v[60:63]
	v_mfma_f32_16x16x32_bf16 v[56:59], v[136:139], v[200:203], v[56:59]
	v_mfma_f32_16x16x32_bf16 v[52:55], v[160:163], v[200:203], v[52:55]
	v_mfma_f32_16x16x32_bf16 v[48:51], v[136:139], v[208:211], v[48:51]
	v_mfma_f32_16x16x32_bf16 v[44:47], v[160:163], v[208:211], v[44:47]
	v_mfma_f32_16x16x32_bf16 v[40:43], v[136:139], v[216:219], v[40:43]
	v_mfma_f32_16x16x32_bf16 v[36:39], v[160:163], v[216:219], v[36:39]
	v_mfma_f32_16x16x32_bf16 v[32:35], v[172:175], v[188:191], 0
	v_mfma_f32_16x16x32_bf16 v[28:31], v[180:183], v[188:191], 0
	v_mfma_f32_16x16x32_bf16 v[24:27], v[172:175], v[196:199], 0
	v_mfma_f32_16x16x32_bf16 v[20:23], v[180:183], v[196:199], 0
	v_mfma_f32_16x16x32_bf16 v[16:19], v[172:175], v[204:207], 0
	v_mfma_f32_16x16x32_bf16 v[12:15], v[180:183], v[204:207], 0
	v_mfma_f32_16x16x32_bf16 v[8:11], v[172:175], v[212:215], 0
	v_mfma_f32_16x16x32_bf16 v[2:5], v[180:183], v[212:215], 0
	v_mfma_f32_16x16x32_bf16 v[32:35], v[176:179], v[192:195], v[32:35]
	v_mfma_f32_16x16x32_bf16 v[28:31], v[184:187], v[192:195], v[28:31]
	v_mfma_f32_16x16x32_bf16 v[24:27], v[176:179], v[200:203], v[24:27]
	v_mfma_f32_16x16x32_bf16 v[20:23], v[184:187], v[200:203], v[20:23]
	v_mfma_f32_16x16x32_bf16 v[16:19], v[176:179], v[208:211], v[16:19]
	v_mfma_f32_16x16x32_bf16 v[12:15], v[184:187], v[208:211], v[12:15]
	v_mfma_f32_16x16x32_bf16 v[8:11], v[176:179], v[216:219], v[8:11]
	v_mfma_f32_16x16x32_bf16 v[2:5], v[184:187], v[216:219], v[2:5]
	s_barrier
	s_branch .Lmid_k966
; #define PG8_STAGE(bufoff, gbase, voff) do { _Pragma("unroll") for (int _i = 0; _i < 2; ++_i) \
;         __builtin_amdgcn_global_load_lds((const unsigned*)((const char*)(gbase) + (voff)[_i]), (PG8_LAS unsigned*)(lds + (bufoff) + ldsw + _i * 8192), 16, 0, 0); } while (0)
; #define PG8_LDA(dst, b, h) do { _Pragma("unroll") for (int m = 0; m < 4; ++m) _Pragma("unroll") for (int k = 0; k < 2; ++k) dst[m][k] = *(const PG8_LAS bf16x8*)(lds + PG8_SA(b, h) + aoff + m * 2048 + k * 1024); } while (0)
; #define PG8_LDB(dst, b, h) do { _Pragma("unroll") for (int n = 0; n < 2; ++n) _Pragma("unroll") for (int k = 0; k < 2; ++k) dst[n][k] = *(const PG8_LAS bf16x8*)(lds + PG8_SB(b, h) + boff + n * 2048 + k * 1024); } while (0)
; #define PG8_WAIT_V(n) asm volatile("s_waitcnt vmcnt(" #n ")" ::: "memory")
; #define PG8_WAIT_L(n) asm volatile("s_waitcnt lgkmcnt(" #n ")" ::: "memory")
; #define PG8_BAR __builtin_amdgcn_s_barrier()
; template <class Epi, class Sched, bool ALIGN_EPI = false, bool SP2 = false, bool F8 = false>
; __device__ __forceinline__ void gemm_phase(PG8_LAS unsigned char* lds, const int K, const Sched& S, const Epi& E, const int wave) {
;     ...
;             const bool last = (t == nt - 2);
;             const char* a1 = cA + (size_t)(t + 1) * kstep;
;             const char* a2 = last ? nA : cA + (size_t)(t + 2) * kstep; const char* b2 = last ? nB : cB + (size_t)(t + 2) * kstep;
;             const char* a3 = a2 + kstep; const char* b3 = b2 + kstep;
;             asm volatile("" : "+s"(a1), "+s"(a2), "+s"(b2), "+s"(a3), "+s"(b3));
;             if (last && has_next) S.a_ready(nxt);
;             if constexpr (Epi::KHOOK) { if (cur.prob == 2 ? (t == 16) : (t == 32 || t == 48)) { if (wr == 0) PG8_BAR;
;                 E.khook(acc, cur, (cur.prob == 2 || t == 48) ? 1 : 0, wr, wc, fr, fq); if (wr == 1) PG8_BAR; } }
;             if constexpr (SP2) {
;             PG8_LDB(B0, 0, 0); PG8_LDB(B1, 0, 1); PG8_SCHED; PG8_LDA(At, 0, 0); PG8_STAGE(PG8_SA(1, 1), a1 + hstep, voffA);
;             PG8_WAIT_V(8); PG8_WAIT_L(0); PG8_BAR; PG8_MMA(0, 0, At, B0); PG8_MMA(0, 1, At, B1); PG8_BAR; PG8_SCHED;
;             PG8_LDA(At, 0, 1); PG8_STAGE(PG8_SB(0, 0), b2, voffB); PG8_STAGE(PG8_SB(0, 1), b2 + hstep, voffB); PG8_STAGE(PG8_SA(0, 0), a2, voffA);
;             PG8_WAIT_V(8); PG8_WAIT_L(0); PG8_BAR; PG8_MMA(1, 0, At, B0); PG8_MMA(1, 1, At, B1); PG8_BAR; PG8_SCHED;
.LBB0_966:
	s_add_i32 s90, s8, 2
	s_cmp_eq_u32 s85, s8
	s_cselect_b32 s42, s31, s86
	s_cselect_b32 s43, s25, s87
	s_cselect_b32 s57, s83, s89
	s_cselect_b32 s56, s84, s88
	s_add_u32 s8, s42, 0x80
	s_addc_u32 s9, s43, 0
	s_add_u32 s40, s56, 0x80
	s_addc_u32 s41, s57, 0
	s_mov_b64 s[92:93], s[6:7]
	v_add_u32_e32 v1, s77, v168
	ds_read_b128 v[132:135], v1
	ds_read_b128 v[136:139], v1 offset:1024
	ds_read_b128 v[156:159], v1 offset:2048
	ds_read_b128 v[160:163], v1 offset:3072
	v_add_u32_e32 v1, s78, v168
	ds_read_b128 v[172:175], v1
	ds_read_b128 v[176:179], v1 offset:1024
	ds_read_b128 v[180:183], v1 offset:2048
	ds_read_b128 v[184:187], v1 offset:3072
	s_add_u32 s92, s92, 0x100000
	s_addc_u32 s93, s93, 0
	s_add_i32 m0, s64, 0xc000
	ds_read_b128 v[188:191], v170
	ds_read_b128 v[192:195], v170 offset:1024
	ds_read_b128 v[196:199], v170 offset:2048
	ds_read_b128 v[200:203], v170 offset:3072
	ds_read_b128 v[204:207], v170 offset:4096
	ds_read_b128 v[208:211], v170 offset:5120
	ds_read_b128 v[212:215], v170 offset:6144
	ds_read_b128 v[216:219], v170 offset:7168
	global_load_lds_dwordx4 v140, s[92:93]
	s_add_i32 m0, s64, 0xe000
	s_nop 0
	global_load_lds_dwordx4 v144, s[92:93]
	s_waitcnt vmcnt(8)
	s_waitcnt lgkmcnt(0)
	s_setprio 1
	s_barrier
	v_mfma_f32_16x16x32_bf16 v[128:131], v[132:135], v[188:191], v[128:131]
	v_mfma_f32_16x16x32_bf16 v[124:127], v[156:159], v[188:191], v[124:127]
	v_mfma_f32_16x16x32_bf16 v[120:123], v[132:135], v[196:199], v[120:123]
	v_mfma_f32_16x16x32_bf16 v[116:119], v[156:159], v[196:199], v[116:119]
	v_mfma_f32_16x16x32_bf16 v[112:115], v[132:135], v[204:207], v[112:115]
	v_mfma_f32_16x16x32_bf16 v[108:111], v[156:159], v[204:207], v[108:111]
	v_mfma_f32_16x16x32_bf16 v[104:107], v[132:135], v[212:215], v[104:107]
	v_mfma_f32_16x16x32_bf16 v[100:103], v[156:159], v[212:215], v[100:103]
	v_mfma_f32_16x16x32_bf16 v[128:131], v[136:139], v[192:195], v[128:131]
	v_mfma_f32_16x16x32_bf16 v[124:127], v[160:163], v[192:195], v[124:127]
	v_mfma_f32_16x16x32_bf16 v[120:123], v[136:139], v[200:203], v[120:123]
	v_mfma_f32_16x16x32_bf16 v[116:119], v[160:163], v[200:203], v[116:119]
	v_mfma_f32_16x16x32_bf16 v[112:115], v[136:139], v[208:211], v[112:115]
	v_mfma_f32_16x16x32_bf16 v[108:111], v[160:163], v[208:211], v[108:111]
	v_mfma_f32_16x16x32_bf16 v[104:107], v[136:139], v[216:219], v[104:107]
	v_mfma_f32_16x16x32_bf16 v[100:103], v[160:163], v[216:219], v[100:103]
	v_mfma_f32_16x16x32_bf16 v[96:99], v[172:175], v[188:191], v[96:99]
	v_mfma_f32_16x16x32_bf16 v[92:95], v[180:183], v[188:191], v[92:95]
	v_mfma_f32_16x16x32_bf16 v[88:91], v[172:175], v[196:199], v[88:91]
	v_mfma_f32_16x16x32_bf16 v[84:87], v[180:183], v[196:199], v[84:87]
	v_mfma_f32_16x16x32_bf16 v[80:83], v[172:175], v[204:207], v[80:83]
	v_mfma_f32_16x16x32_bf16 v[76:79], v[180:183], v[204:207], v[76:79]
	v_mfma_f32_16x16x32_bf16 v[72:75], v[172:175], v[212:215], v[72:75]
	v_mfma_f32_16x16x32_bf16 v[68:71], v[180:183], v[212:215], v[68:71]
	v_mfma_f32_16x16x32_bf16 v[96:99], v[176:179], v[192:195], v[96:99]
	v_mfma_f32_16x16x32_bf16 v[92:95], v[184:187], v[192:195], v[92:95]
	v_mfma_f32_16x16x32_bf16 v[88:91], v[176:179], v[200:203], v[88:91]
	v_mfma_f32_16x16x32_bf16 v[84:87], v[184:187], v[200:203], v[84:87]
	v_mfma_f32_16x16x32_bf16 v[80:83], v[176:179], v[208:211], v[80:83]
	v_mfma_f32_16x16x32_bf16 v[76:79], v[184:187], v[208:211], v[76:79]
	v_mfma_f32_16x16x32_bf16 v[72:75], v[176:179], v[216:219], v[72:75]
	v_mfma_f32_16x16x32_bf16 v[68:71], v[184:187], v[216:219], v[68:71]
	s_barrier
	s_setprio 0
	s_add_i32 s91, s77, s63
	s_mov_b32 m0, s91
	ds_read_b128 v[188:191], v170 offset:16384
	ds_read_b128 v[192:195], v170 offset:17408
	ds_read_b128 v[196:199], v170 offset:18432
	ds_read_b128 v[200:203], v170 offset:19456
	ds_read_b128 v[204:207], v170 offset:20480
	ds_read_b128 v[208:211], v170 offset:21504
	ds_read_b128 v[212:215], v170 offset:22528
	ds_read_b128 v[216:219], v170 offset:23552
	global_load_lds_dwordx4 v142, s[56:57]
	s_add_i32 m0, s91, 0x2000
	s_nop 0
	global_load_lds_dwordx4 v146, s[56:57]
	s_add_u32 s56, s56, 0x100000
	s_addc_u32 s57, s57, 0
	s_add_i32 s91, s78, s63
	s_mov_b32 m0, s91
	s_nop 0
	global_load_lds_dwordx4 v142, s[56:57]
	s_add_i32 m0, s91, 0x2000
	s_nop 0
	global_load_lds_dwordx4 v146, s[56:57]
	s_mov_b32 m0, s64
	s_nop 0
	global_load_lds_dwordx4 v140, s[42:43]
	s_mov_b32 m0, s65
	s_nop 0
	global_load_lds_dwordx4 v144, s[42:43]
	s_waitcnt vmcnt(8)
	s_waitcnt lgkmcnt(0)
	s_setprio 1
	s_barrier
	v_mfma_f32_16x16x32_bf16 v[64:67], v[132:135], v[188:191], v[64:67]
	v_mfma_f32_16x16x32_bf16 v[60:63], v[156:159], v[188:191], v[60:63]
	v_mfma_f32_16x16x32_bf16 v[56:59], v[132:135], v[196:199], v[56:59]
	v_mfma_f32_16x16x32_bf16 v[52:55], v[156:159], v[196:199], v[52:55]
	v_mfma_f32_16x16x32_bf16 v[48:51], v[132:135], v[204:207], v[48:51]
	v_mfma_f32_16x16x32_bf16 v[44:47], v[156:159], v[204:207], v[44:47]
	v_mfma_f32_16x16x32_bf16 v[40:43], v[132:135], v[212:215], v[40:43]
	v_mfma_f32_16x16x32_bf16 v[36:39], v[156:159], v[212:215], v[36:39]
	v_mfma_f32_16x16x32_bf16 v[64:67], v[136:139], v[192:195], v[64:67]
	v_mfma_f32_16x16x32_bf16 v[60:63], v[160:163], v[192:195], v[60:63]
	v_mfma_f32_16x16x32_bf16 v[56:59], v[136:139], v[200:203], v[56:59]
	v_mfma_f32_16x16x32_bf16 v[52:55], v[160:163], v[200:203], v[52:55]
	v_mfma_f32_16x16x32_bf16 v[48:51], v[136:139], v[208:211], v[48:51]
	v_mfma_f32_16x16x32_bf16 v[44:47], v[160:163], v[208:211], v[44:47]
	v_mfma_f32_16x16x32_bf16 v[40:43], v[136:139], v[216:219], v[40:43]
	v_mfma_f32_16x16x32_bf16 v[36:39], v[160:163], v[216:219], v[36:39]
	v_mfma_f32_16x16x32_bf16 v[32:35], v[172:175], v[188:191], v[32:35]
	v_mfma_f32_16x16x32_bf16 v[28:31], v[180:183], v[188:191], v[28:31]
	v_mfma_f32_16x16x32_bf16 v[24:27], v[172:175], v[196:199], v[24:27]
	v_mfma_f32_16x16x32_bf16 v[20:23], v[180:183], v[196:199], v[20:23]
	v_mfma_f32_16x16x32_bf16 v[16:19], v[172:175], v[204:207], v[16:19]
	v_mfma_f32_16x16x32_bf16 v[12:15], v[180:183], v[204:207], v[12:15]
	v_mfma_f32_16x16x32_bf16 v[8:11], v[172:175], v[212:215], v[8:11]
	v_mfma_f32_16x16x32_bf16 v[2:5], v[180:183], v[212:215], v[4:7]
	v_mfma_f32_16x16x32_bf16 v[32:35], v[176:179], v[192:195], v[32:35]
	v_mfma_f32_16x16x32_bf16 v[28:31], v[184:187], v[192:195], v[28:31]
	v_mfma_f32_16x16x32_bf16 v[24:27], v[176:179], v[200:203], v[24:27]
	v_mfma_f32_16x16x32_bf16 v[20:23], v[184:187], v[200:203], v[20:23]
	v_mfma_f32_16x16x32_bf16 v[16:19], v[176:179], v[208:211], v[16:19]
	v_mfma_f32_16x16x32_bf16 v[12:15], v[184:187], v[208:211], v[12:15]
	v_mfma_f32_16x16x32_bf16 v[8:11], v[176:179], v[216:219], v[8:11]
	v_mfma_f32_16x16x32_bf16 v[2:5], v[184:187], v[216:219], v[2:5]
	s_barrier
; #define PG8_STAGE(bufoff, gbase, voff) do { _Pragma("unroll") for (int _i = 0; _i < 2; ++_i) \
;         __builtin_amdgcn_global_load_lds((const unsigned*)((const char*)(gbase) + (voff)[_i]), (PG8_LAS unsigned*)(lds + (bufoff) + ldsw + _i * 8192), 16, 0, 0); } while (0)
; #define PG8_LDA(dst, b, h) do { _Pragma("unroll") for (int m = 0; m < 4; ++m) _Pragma("unroll") for (int k = 0; k < 2; ++k) dst[m][k] = *(const PG8_LAS bf16x8*)(lds + PG8_SA(b, h) + aoff + m * 2048 + k * 1024); } while (0)
; #define PG8_LDB(dst, b, h) do { _Pragma("unroll") for (int n = 0; n < 2; ++n) _Pragma("unroll") for (int k = 0; k < 2; ++k) dst[n][k] = *(const PG8_LAS bf16x8*)(lds + PG8_SB(b, h) + boff + n * 2048 + k * 1024); } while (0)
; #define PG8_WAIT_V(n) asm volatile("s_waitcnt vmcnt(" #n ")" ::: "memory")
; #define PG8_WAIT_L(n) asm volatile("s_waitcnt lgkmcnt(" #n ")" ::: "memory")
; #define PG8_BAR __builtin_amdgcn_s_barrier()
; #define PG8_SCHED __builtin_amdgcn_sched_barrier(0)
; template <class Epi, class Sched, bool ALIGN_EPI = false, bool SP2 = false, bool F8 = false>
; __device__ __forceinline__ void gemm_phase(PG8_LAS unsigned char* lds, const int K, const Sched& S, const Epi& E, const int wave) {
;     ...
;         for (int t = 0; t < nt; t += 2) {
;             const bool last = (t == nt - 2);
;             const char* a1 = cA + (size_t)(t + 1) * kstep;
;             const char* a2 = last ? nA : cA + (size_t)(t + 2) * kstep; const char* b2 = last ? nB : cB + (size_t)(t + 2) * kstep;
;             const char* a3 = a2 + kstep; const char* b3 = b2 + kstep;
;     ...
;             PG8_LDB(B0, 1, 0); PG8_LDB(B1, 1, 1); PG8_SCHED; PG8_LDA(At, 1, 0); PG8_STAGE(PG8_SA(0, 1), a2 + hstep, voffA);
;             PG8_WAIT_V(8); PG8_WAIT_L(0); PG8_BAR; PG8_MMA(0, 0, At, B0); PG8_MMA(0, 1, At, B1); PG8_BAR; PG8_SCHED;
;             PG8_LDA(At, 1, 1); PG8_STAGE(PG8_SB(1, 0), b3, voffB); PG8_STAGE(PG8_SB(1, 1), b3 + hstep, voffB); PG8_STAGE(PG8_SA(1, 0), a3, voffA);
;             PG8_WAIT_V(8); PG8_WAIT_L(0); PG8_BAR; PG8_MMA(1, 0, At, B0); PG8_MMA(1, 1, At, B1); PG8_BAR; PG8_SCHED;
.Lmid_k966:
	s_setprio 0
	s_add_i32 s56, 0, 0x18000
	v_add_u32_e32 v1, s56, v168
	s_add_i32 s57, 0, 0x1c000
	ds_read_b128 v[132:135], v1
	ds_read_b128 v[136:139], v1 offset:1024
	ds_read_b128 v[156:159], v1 offset:2048
	ds_read_b128 v[160:163], v1 offset:3072
	v_add_u32_e32 v1, s57, v168
	ds_read_b128 v[172:175], v1
	ds_read_b128 v[176:179], v1 offset:1024
	ds_read_b128 v[180:183], v1 offset:2048
	ds_read_b128 v[184:187], v1 offset:3072
	s_add_u32 s42, s42, 0x100000
	s_addc_u32 s43, s43, 0
	s_mov_b32 m0, s66
	ds_read_b128 v[188:191], v170 offset:32768
	ds_read_b128 v[192:195], v170 offset:33792
	ds_read_b128 v[196:199], v170 offset:34816
	ds_read_b128 v[200:203], v170 offset:35840
	ds_read_b128 v[204:207], v170 offset:36864
	ds_read_b128 v[208:211], v170 offset:37888
	ds_read_b128 v[212:215], v170 offset:38912
	ds_read_b128 v[216:219], v170 offset:39936
	global_load_lds_dwordx4 v140, s[42:43]
	s_mov_b32 m0, s67
	s_nop 0
	global_load_lds_dwordx4 v144, s[42:43]
	s_waitcnt vmcnt(8)
	s_waitcnt lgkmcnt(0)
	s_setprio 1
	s_barrier
	v_mfma_f32_16x16x32_bf16 v[128:131], v[132:135], v[188:191], v[128:131]
	v_mfma_f32_16x16x32_bf16 v[124:127], v[156:159], v[188:191], v[124:127]
	v_mfma_f32_16x16x32_bf16 v[120:123], v[132:135], v[196:199], v[120:123]
	v_mfma_f32_16x16x32_bf16 v[116:119], v[156:159], v[196:199], v[116:119]
	v_mfma_f32_16x16x32_bf16 v[112:115], v[132:135], v[204:207], v[112:115]
	v_mfma_f32_16x16x32_bf16 v[108:111], v[156:159], v[204:207], v[108:111]
	v_mfma_f32_16x16x32_bf16 v[104:107], v[132:135], v[212:215], v[104:107]
	v_mfma_f32_16x16x32_bf16 v[100:103], v[156:159], v[212:215], v[100:103]
	v_mfma_f32_16x16x32_bf16 v[128:131], v[136:139], v[192:195], v[128:131]
	v_mfma_f32_16x16x32_bf16 v[124:127], v[160:163], v[192:195], v[124:127]
	v_mfma_f32_16x16x32_bf16 v[120:123], v[136:139], v[200:203], v[120:123]
	v_mfma_f32_16x16x32_bf16 v[116:119], v[160:163], v[200:203], v[116:119]
	v_mfma_f32_16x16x32_bf16 v[112:115], v[136:139], v[208:211], v[112:115]
	v_mfma_f32_16x16x32_bf16 v[108:111], v[160:163], v[208:211], v[108:111]
	v_mfma_f32_16x16x32_bf16 v[104:107], v[136:139], v[216:219], v[104:107]
	v_mfma_f32_16x16x32_bf16 v[100:103], v[160:163], v[216:219], v[100:103]
	v_mfma_f32_16x16x32_bf16 v[96:99], v[172:175], v[188:191], v[96:99]
	v_mfma_f32_16x16x32_bf16 v[92:95], v[180:183], v[188:191], v[92:95]
	v_mfma_f32_16x16x32_bf16 v[88:91], v[172:175], v[196:199], v[88:91]
	v_mfma_f32_16x16x32_bf16 v[84:87], v[180:183], v[196:199], v[84:87]
	v_mfma_f32_16x16x32_bf16 v[80:83], v[172:175], v[204:207], v[80:83]
	v_mfma_f32_16x16x32_bf16 v[76:79], v[180:183], v[204:207], v[76:79]
	v_mfma_f32_16x16x32_bf16 v[72:75], v[172:175], v[212:215], v[72:75]
	v_mfma_f32_16x16x32_bf16 v[68:71], v[180:183], v[212:215], v[68:71]
	v_mfma_f32_16x16x32_bf16 v[96:99], v[176:179], v[192:195], v[96:99]
	v_mfma_f32_16x16x32_bf16 v[92:95], v[184:187], v[192:195], v[92:95]
	v_mfma_f32_16x16x32_bf16 v[88:91], v[176:179], v[200:203], v[88:91]
	v_mfma_f32_16x16x32_bf16 v[84:87], v[184:187], v[200:203], v[84:87]
	v_mfma_f32_16x16x32_bf16 v[80:83], v[176:179], v[208:211], v[80:83]
	v_mfma_f32_16x16x32_bf16 v[76:79], v[184:187], v[208:211], v[76:79]
	v_mfma_f32_16x16x32_bf16 v[72:75], v[176:179], v[216:219], v[72:75]
	v_mfma_f32_16x16x32_bf16 v[68:71], v[184:187], v[216:219], v[68:71]
	s_barrier
	s_setprio 0
	s_add_i32 s42, s56, s63
	s_mov_b32 m0, s42
	ds_read_b128 v[188:191], v170 offset:49152
	ds_read_b128 v[192:195], v170 offset:50176
	ds_read_b128 v[196:199], v170 offset:51200
	ds_read_b128 v[200:203], v170 offset:52224
	ds_read_b128 v[204:207], v170 offset:53248
	ds_read_b128 v[208:211], v170 offset:54272
	ds_read_b128 v[212:215], v170 offset:55296
	ds_read_b128 v[216:219], v170 offset:56320
	global_load_lds_dwordx4 v142, s[40:41]
	s_add_i32 m0, s42, 0x2000
	s_nop 0
	global_load_lds_dwordx4 v146, s[40:41]
	s_add_u32 s40, s40, 0x100000
	s_addc_u32 s41, s41, 0
	s_add_i32 s42, s57, s63
	s_mov_b32 m0, s42
	s_nop 0
	global_load_lds_dwordx4 v142, s[40:41]
	s_add_i32 m0, s42, 0x2000
	s_nop 0
	global_load_lds_dwordx4 v146, s[40:41]
	s_mov_b32 m0, s74
	s_nop 0
	global_load_lds_dwordx4 v140, s[8:9]
	s_mov_b32 m0, s76
	s_nop 0
	global_load_lds_dwordx4 v144, s[8:9]
	s_waitcnt vmcnt(8)
	s_waitcnt lgkmcnt(0)
	s_setprio 1
	s_barrier
	v_mfma_f32_16x16x32_bf16 v[64:67], v[132:135], v[188:191], v[64:67]
	v_mfma_f32_16x16x32_bf16 v[60:63], v[156:159], v[188:191], v[60:63]
	v_mfma_f32_16x16x32_bf16 v[56:59], v[132:135], v[196:199], v[56:59]
	v_mfma_f32_16x16x32_bf16 v[52:55], v[156:159], v[196:199], v[52:55]
	v_mfma_f32_16x16x32_bf16 v[48:51], v[132:135], v[204:207], v[48:51]
	v_mfma_f32_16x16x32_bf16 v[44:47], v[156:159], v[204:207], v[44:47]
	v_mfma_f32_16x16x32_bf16 v[40:43], v[132:135], v[212:215], v[40:43]
	v_mfma_f32_16x16x32_bf16 v[36:39], v[156:159], v[212:215], v[36:39]
	v_mfma_f32_16x16x32_bf16 v[64:67], v[136:139], v[192:195], v[64:67]
	v_mfma_f32_16x16x32_bf16 v[60:63], v[160:163], v[192:195], v[60:63]
	v_mfma_f32_16x16x32_bf16 v[56:59], v[136:139], v[200:203], v[56:59]
	v_mfma_f32_16x16x32_bf16 v[52:55], v[160:163], v[200:203], v[52:55]
	v_mfma_f32_16x16x32_bf16 v[48:51], v[136:139], v[208:211], v[48:51]
	v_mfma_f32_16x16x32_bf16 v[44:47], v[160:163], v[208:211], v[44:47]
	v_mfma_f32_16x16x32_bf16 v[40:43], v[136:139], v[216:219], v[40:43]
	v_mfma_f32_16x16x32_bf16 v[36:39], v[160:163], v[216:219], v[36:39]
	v_mfma_f32_16x16x32_bf16 v[32:35], v[172:175], v[188:191], v[32:35]
	v_mfma_f32_16x16x32_bf16 v[28:31], v[180:183], v[188:191], v[28:31]
	v_mfma_f32_16x16x32_bf16 v[24:27], v[172:175], v[196:199], v[24:27]
	v_mfma_f32_16x16x32_bf16 v[20:23], v[180:183], v[196:199], v[20:23]
	v_mfma_f32_16x16x32_bf16 v[16:19], v[172:175], v[204:207], v[16:19]
	v_mfma_f32_16x16x32_bf16 v[12:15], v[180:183], v[204:207], v[12:15]
	v_mfma_f32_16x16x32_bf16 v[6:9], v[172:175], v[212:215], v[8:11]
	v_mfma_f32_16x16x32_bf16 v[2:5], v[180:183], v[212:215], v[2:5]
	v_mfma_f32_16x16x32_bf16 v[32:35], v[176:179], v[192:195], v[32:35]
	v_mfma_f32_16x16x32_bf16 v[28:31], v[184:187], v[192:195], v[28:31]
	v_mfma_f32_16x16x32_bf16 v[24:27], v[176:179], v[200:203], v[24:27]
	v_mfma_f32_16x16x32_bf16 v[20:23], v[184:187], v[200:203], v[20:23]
	v_mfma_f32_16x16x32_bf16 v[16:19], v[176:179], v[208:211], v[16:19]
	v_mfma_f32_16x16x32_bf16 v[12:15], v[184:187], v[208:211], v[12:15]
	v_mfma_f32_16x16x32_bf16 v[8:11], v[176:179], v[216:219], v[6:9]
	v_mfma_f32_16x16x32_bf16 v[4:7], v[184:187], v[216:219], v[2:5]
	s_barrier
	s_setprio 0
	s_add_u32 s86, s86, 0x100
	s_addc_u32 s87, s87, 0
	s_add_u32 s88, s88, 0x100
	s_addc_u32 s89, s89, 0
	s_add_u32 s6, s6, 0x100
	s_addc_u32 s7, s7, 0
	s_cmp_ge_i32 s90, s62
	s_mov_b32 s8, s90
	s_cbranch_scc0 .LBB0_966

; #define PG8_STAGE(bufoff, gbase, voff) do { _Pragma("unroll") for (int _i = 0; _i < 2; ++_i) \
;         __builtin_amdgcn_global_load_lds((const unsigned*)((const char*)(gbase) + (voff)[_i]), (PG8_LAS unsigned*)(lds + (bufoff) + ldsw + _i * 8192), 16, 0, 0); } while (0)
; #define PG8_LDA(dst, b, h) do { _Pragma("unroll") for (int m = 0; m < 4; ++m) _Pragma("unroll") for (int k = 0; k < 2; ++k) dst[m][k] = *(const PG8_LAS bf16x8*)(lds + PG8_SA(b, h) + aoff + m * 2048 + k * 1024); } while (0)
; #define PG8_LDB(dst, b, h) do { _Pragma("unroll") for (int n = 0; n < 2; ++n) _Pragma("unroll") for (int k = 0; k < 2; ++k) dst[n][k] = *(const PG8_LAS bf16x8*)(lds + PG8_SB(b, h) + boff + n * 2048 + k * 1024); } while (0)
; #define PG8_WAIT_V(n) asm volatile("s_waitcnt vmcnt(" #n ")" ::: "memory")
; #define PG8_WAIT_L(n) asm volatile("s_waitcnt lgkmcnt(" #n ")" ::: "memory")
; #define PG8_BAR __builtin_amdgcn_s_barrier()
; template <class Epi, class Sched, bool ALIGN_EPI = false, bool SP2 = false, bool F8 = false>
; __device__ __forceinline__ void gemm_phase(PG8_LAS unsigned char* lds, const int K, const Sched& S, const Epi& E, const int wave) {
;     ...
;             const bool last = (t == nt - 2);
;             const char* a1 = cA + (size_t)(t + 1) * kstep;
;             const char* a2 = last ? nA : cA + (size_t)(t + 2) * kstep; const char* b2 = last ? nB : cB + (size_t)(t + 2) * kstep;
;             const char* a3 = a2 + kstep; const char* b3 = b2 + kstep;
;             asm volatile("" : "+s"(a1), "+s"(a2), "+s"(b2), "+s"(a3), "+s"(b3));
;             if (last && has_next) S.a_ready(nxt);
;             if constexpr (Epi::KHOOK) { if (cur.prob == 2 ? (t == 16) : (t == 32 || t == 48)) { if (wr == 0) PG8_BAR;
;                 E.khook(acc, cur, (cur.prob == 2 || t == 48) ? 1 : 0, wr, wc, fr, fq); if (wr == 1) PG8_BAR; } }
;             if constexpr (SP2) {
;             PG8_LDB(B0, 0, 0); PG8_LDB(B1, 0, 1); PG8_SCHED; PG8_LDA(At, 0, 0); PG8_STAGE(PG8_SA(1, 1), a1 + hstep, voffA);
;             PG8_WAIT_V(8); PG8_WAIT_L(0); PG8_BAR; PG8_MMA(0, 0, At, B0); PG8_MMA(0, 1, At, B1); PG8_BAR; PG8_SCHED;
;             PG8_LDA(At, 0, 1); PG8_STAGE(PG8_SB(0, 0), b2, voffB); PG8_STAGE(PG8_SB(0, 1), b2 + hstep, voffB); PG8_STAGE(PG8_SA(0, 0), a2, voffA);
;             PG8_WAIT_V(8); PG8_WAIT_L(0); PG8_BAR; PG8_MMA(1, 0, At, B0); PG8_MMA(1, 1, At, B1); PG8_BAR; PG8_SCHED;
.Lpeel_k1240:
	s_add_u32 s25, s10, s38
	s_addc_u32 s40, s11, s39
	s_add_u32 s64, s25, 0xffffff80
	s_addc_u32 s65, s40, -1
	s_add_u32 s41, s12, s38
	s_addc_u32 s42, s13, s39
	s_cmp_eq_u32 s23, 60
	s_cselect_b32 s44, s30, s25
	s_cselect_b32 s45, s31, s40
	s_cselect_b32 s53, s37, s42
	s_cselect_b32 s52, s36, s41
	s_add_u32 s40, s44, 0x80
	s_addc_u32 s41, s45, 0
	s_add_u32 s42, s52, 0x80
	s_addc_u32 s43, s53, 0
	v_add_u32_e32 v149, s59, v146
	ds_read_b128 v[140:143], v149
	ds_read_b128 v[150:153], v149 offset:1024
	ds_read_b128 v[154:157], v149 offset:2048
	ds_read_b128 v[158:161], v149 offset:3072
	v_add_u32_e32 v149, s60, v146
	ds_read_b128 v[162:165], v149
	ds_read_b128 v[166:169], v149 offset:1024
	ds_read_b128 v[170:173], v149 offset:2048
	ds_read_b128 v[174:177], v149 offset:3072
	s_add_u32 s64, s64, 0x100000
	s_addc_u32 s65, s65, 0
	s_add_i32 m0, s9, 0xc000
	ds_read_b128 v[178:181], v148
	ds_read_b128 v[182:185], v148 offset:1024
	ds_read_b128 v[186:189], v148 offset:2048
	ds_read_b128 v[190:193], v148 offset:3072
	ds_read_b128 v[194:197], v148 offset:4096
	ds_read_b128 v[198:201], v148 offset:5120
	ds_read_b128 v[202:205], v148 offset:6144
	ds_read_b128 v[206:209], v148 offset:7168
	global_load_lds_dwordx4 v134, s[64:65]
	s_add_i32 m0, s9, 0xe000
	s_nop 0
	global_load_lds_dwordx4 v130, s[64:65]
	s_waitcnt vmcnt(8)
	s_waitcnt lgkmcnt(0)
	s_setprio 1
	s_barrier
	v_mfma_f32_16x16x32_bf16 v[124:127], v[140:143], v[178:181], 0
	v_mfma_f32_16x16x32_bf16 v[120:123], v[154:157], v[178:181], 0
	v_mfma_f32_16x16x32_bf16 v[116:119], v[140:143], v[186:189], 0
	v_mfma_f32_16x16x32_bf16 v[112:115], v[154:157], v[186:189], 0
	v_mfma_f32_16x16x32_bf16 v[108:111], v[140:143], v[194:197], 0
	v_mfma_f32_16x16x32_bf16 v[104:107], v[154:157], v[194:197], 0
	v_mfma_f32_16x16x32_bf16 v[100:103], v[140:143], v[202:205], 0
	v_mfma_f32_16x16x32_bf16 v[96:99], v[154:157], v[202:205], 0
	v_mfma_f32_16x16x32_bf16 v[124:127], v[150:153], v[182:185], v[124:127]
	v_mfma_f32_16x16x32_bf16 v[120:123], v[158:161], v[182:185], v[120:123]
	v_mfma_f32_16x16x32_bf16 v[116:119], v[150:153], v[190:193], v[116:119]
	v_mfma_f32_16x16x32_bf16 v[112:115], v[158:161], v[190:193], v[112:115]
	v_mfma_f32_16x16x32_bf16 v[108:111], v[150:153], v[198:201], v[108:111]
	v_mfma_f32_16x16x32_bf16 v[104:107], v[158:161], v[198:201], v[104:107]
	v_mfma_f32_16x16x32_bf16 v[100:103], v[150:153], v[206:209], v[100:103]
	v_mfma_f32_16x16x32_bf16 v[96:99], v[158:161], v[206:209], v[96:99]
	v_mfma_f32_16x16x32_bf16 v[92:95], v[162:165], v[178:181], 0
	v_mfma_f32_16x16x32_bf16 v[88:91], v[170:173], v[178:181], 0
	v_mfma_f32_16x16x32_bf16 v[84:87], v[162:165], v[186:189], 0
	v_mfma_f32_16x16x32_bf16 v[80:83], v[170:173], v[186:189], 0
	v_mfma_f32_16x16x32_bf16 v[76:79], v[162:165], v[194:197], 0
	v_mfma_f32_16x16x32_bf16 v[72:75], v[170:173], v[194:197], 0
	v_mfma_f32_16x16x32_bf16 v[68:71], v[162:165], v[202:205], 0
	v_mfma_f32_16x16x32_bf16 v[64:67], v[170:173], v[202:205], 0
	v_mfma_f32_16x16x32_bf16 v[92:95], v[166:169], v[182:185], v[92:95]
	v_mfma_f32_16x16x32_bf16 v[88:91], v[174:177], v[182:185], v[88:91]
	v_mfma_f32_16x16x32_bf16 v[84:87], v[166:169], v[190:193], v[84:87]
	v_mfma_f32_16x16x32_bf16 v[80:83], v[174:177], v[190:193], v[80:83]
	v_mfma_f32_16x16x32_bf16 v[76:79], v[166:169], v[198:201], v[76:79]
	v_mfma_f32_16x16x32_bf16 v[72:75], v[174:177], v[198:201], v[72:75]
	v_mfma_f32_16x16x32_bf16 v[68:71], v[166:169], v[206:209], v[68:71]
	v_mfma_f32_16x16x32_bf16 v[64:67], v[174:177], v[206:209], v[64:67]
	s_barrier
	s_setprio 0
	s_add_i32 s25, s59, s48
	s_mov_b32 m0, s25
	ds_read_b128 v[178:181], v148 offset:16384
	ds_read_b128 v[182:185], v148 offset:17408
	ds_read_b128 v[186:189], v148 offset:18432
	ds_read_b128 v[190:193], v148 offset:19456
	ds_read_b128 v[194:197], v148 offset:20480
	ds_read_b128 v[198:201], v148 offset:21504
	ds_read_b128 v[202:205], v148 offset:22528
	ds_read_b128 v[206:209], v148 offset:23552
	global_load_lds_dwordx4 v132, s[52:53]
	s_add_i32 m0, s25, 0x2000
	s_nop 0
	global_load_lds_dwordx4 v128, s[52:53]
	s_add_u32 s52, s52, 0x100000
	s_addc_u32 s53, s53, 0
	s_add_i32 s25, s60, s48
	s_mov_b32 m0, s25
	s_nop 0
	global_load_lds_dwordx4 v132, s[52:53]
	s_add_i32 m0, s25, 0x2000
	s_nop 0
	global_load_lds_dwordx4 v128, s[52:53]
	s_mov_b32 m0, s9
	s_nop 0
	global_load_lds_dwordx4 v134, s[44:45]
	s_mov_b32 m0, s50
	s_nop 0
	global_load_lds_dwordx4 v130, s[44:45]
	s_waitcnt vmcnt(8)
	s_waitcnt lgkmcnt(0)
	s_setprio 1
	s_barrier
	v_mfma_f32_16x16x32_bf16 v[60:63], v[140:143], v[178:181], 0
	v_mfma_f32_16x16x32_bf16 v[56:59], v[154:157], v[178:181], 0
	v_mfma_f32_16x16x32_bf16 v[52:55], v[140:143], v[186:189], 0
	v_mfma_f32_16x16x32_bf16 v[48:51], v[154:157], v[186:189], 0
	v_mfma_f32_16x16x32_bf16 v[44:47], v[140:143], v[194:197], 0
	v_mfma_f32_16x16x32_bf16 v[40:43], v[154:157], v[194:197], 0
	v_mfma_f32_16x16x32_bf16 v[36:39], v[140:143], v[202:205], 0
	v_mfma_f32_16x16x32_bf16 v[32:35], v[154:157], v[202:205], 0
	v_mfma_f32_16x16x32_bf16 v[60:63], v[150:153], v[182:185], v[60:63]
	v_mfma_f32_16x16x32_bf16 v[56:59], v[158:161], v[182:185], v[56:59]
	v_mfma_f32_16x16x32_bf16 v[52:55], v[150:153], v[190:193], v[52:55]
	v_mfma_f32_16x16x32_bf16 v[48:51], v[158:161], v[190:193], v[48:51]
	v_mfma_f32_16x16x32_bf16 v[44:47], v[150:153], v[198:201], v[44:47]
	v_mfma_f32_16x16x32_bf16 v[40:43], v[158:161], v[198:201], v[40:43]
	v_mfma_f32_16x16x32_bf16 v[36:39], v[150:153], v[206:209], v[36:39]
	v_mfma_f32_16x16x32_bf16 v[32:35], v[158:161], v[206:209], v[32:35]
	v_mfma_f32_16x16x32_bf16 v[28:31], v[162:165], v[178:181], 0
	v_mfma_f32_16x16x32_bf16 v[24:27], v[170:173], v[178:181], 0
	v_mfma_f32_16x16x32_bf16 v[20:23], v[162:165], v[186:189], 0
	v_mfma_f32_16x16x32_bf16 v[16:19], v[170:173], v[186:189], 0
	v_mfma_f32_16x16x32_bf16 v[12:15], v[162:165], v[194:197], 0
	v_mfma_f32_16x16x32_bf16 v[8:11], v[170:173], v[194:197], 0
	v_mfma_f32_16x16x32_bf16 v[4:7], v[162:165], v[202:205], 0
	v_mfma_f32_16x16x32_bf16 v[0:3], v[170:173], v[202:205], 0
	v_mfma_f32_16x16x32_bf16 v[28:31], v[166:169], v[182:185], v[28:31]
	v_mfma_f32_16x16x32_bf16 v[24:27], v[174:177], v[182:185], v[24:27]
	v_mfma_f32_16x16x32_bf16 v[20:23], v[166:169], v[190:193], v[20:23]
	v_mfma_f32_16x16x32_bf16 v[16:19], v[174:177], v[190:193], v[16:19]
	v_mfma_f32_16x16x32_bf16 v[12:15], v[166:169], v[198:201], v[12:15]
	v_mfma_f32_16x16x32_bf16 v[8:11], v[174:177], v[198:201], v[8:11]
	v_mfma_f32_16x16x32_bf16 v[4:7], v[166:169], v[206:209], v[4:7]
	v_mfma_f32_16x16x32_bf16 v[0:3], v[174:177], v[206:209], v[0:3]
	s_barrier
	s_branch .Lmid_k1240
; #define PG8_STAGE(bufoff, gbase, voff) do { _Pragma("unroll") for (int _i = 0; _i < 2; ++_i) \
;         __builtin_amdgcn_global_load_lds((const unsigned*)((const char*)(gbase) + (voff)[_i]), (PG8_LAS unsigned*)(lds + (bufoff) + ldsw + _i * 8192), 16, 0, 0); } while (0)
; #define PG8_LDA(dst, b, h) do { _Pragma("unroll") for (int m = 0; m < 4; ++m) _Pragma("unroll") for (int k = 0; k < 2; ++k) dst[m][k] = *(const PG8_LAS bf16x8*)(lds + PG8_SA(b, h) + aoff + m * 2048 + k * 1024); } while (0)
; #define PG8_LDB(dst, b, h) do { _Pragma("unroll") for (int n = 0; n < 2; ++n) _Pragma("unroll") for (int k = 0; k < 2; ++k) dst[n][k] = *(const PG8_LAS bf16x8*)(lds + PG8_SB(b, h) + boff + n * 2048 + k * 1024); } while (0)
; #define PG8_WAIT_V(n) asm volatile("s_waitcnt vmcnt(" #n ")" ::: "memory")
; #define PG8_WAIT_L(n) asm volatile("s_waitcnt lgkmcnt(" #n ")" ::: "memory")
; #define PG8_BAR __builtin_amdgcn_s_barrier()
; template <class Epi, class Sched, bool ALIGN_EPI = false, bool SP2 = false, bool F8 = false>
; __device__ __forceinline__ void gemm_phase(PG8_LAS unsigned char* lds, const int K, const Sched& S, const Epi& E, const int wave) {
;     ...
;             const bool last = (t == nt - 2);
;             const char* a1 = cA + (size_t)(t + 1) * kstep;
;             const char* a2 = last ? nA : cA + (size_t)(t + 2) * kstep; const char* b2 = last ? nB : cB + (size_t)(t + 2) * kstep;
;             const char* a3 = a2 + kstep; const char* b3 = b2 + kstep;
;             asm volatile("" : "+s"(a1), "+s"(a2), "+s"(b2), "+s"(a3), "+s"(b3));
;             if (last && has_next) S.a_ready(nxt);
;             if constexpr (Epi::KHOOK) { if (cur.prob == 2 ? (t == 16) : (t == 32 || t == 48)) { if (wr == 0) PG8_BAR;
;                 E.khook(acc, cur, (cur.prob == 2 || t == 48) ? 1 : 0, wr, wc, fr, fq); if (wr == 1) PG8_BAR; } }
;             if constexpr (SP2) {
;             PG8_LDB(B0, 0, 0); PG8_LDB(B1, 0, 1); PG8_SCHED; PG8_LDA(At, 0, 0); PG8_STAGE(PG8_SA(1, 1), a1 + hstep, voffA);
;             PG8_WAIT_V(8); PG8_WAIT_L(0); PG8_BAR; PG8_MMA(0, 0, At, B0); PG8_MMA(0, 1, At, B1); PG8_BAR; PG8_SCHED;
;             PG8_LDA(At, 0, 1); PG8_STAGE(PG8_SB(0, 0), b2, voffB); PG8_STAGE(PG8_SB(0, 1), b2 + hstep, voffB); PG8_STAGE(PG8_SA(0, 0), a2, voffA);
;             PG8_WAIT_V(8); PG8_WAIT_L(0); PG8_BAR; PG8_MMA(1, 0, At, B0); PG8_MMA(1, 1, At, B1); PG8_BAR; PG8_SCHED;
.LBB0_1240:
	s_add_u32 s25, s10, s38
	s_addc_u32 s40, s11, s39
	s_add_u32 s64, s25, 0xffffff80
	s_addc_u32 s65, s40, -1
	s_add_u32 s41, s12, s38
	s_addc_u32 s42, s13, s39
	s_cmp_eq_u32 s23, 60
	s_cselect_b32 s44, s30, s25
	s_cselect_b32 s45, s31, s40
	s_cselect_b32 s53, s37, s42
	s_cselect_b32 s52, s36, s41
	s_add_u32 s40, s44, 0x80
	s_addc_u32 s41, s45, 0
	s_add_u32 s42, s52, 0x80
	s_addc_u32 s43, s53, 0
	v_add_u32_e32 v149, s59, v146
	ds_read_b128 v[140:143], v149
	ds_read_b128 v[150:153], v149 offset:1024
	ds_read_b128 v[154:157], v149 offset:2048
	ds_read_b128 v[158:161], v149 offset:3072
	v_add_u32_e32 v149, s60, v146
	ds_read_b128 v[162:165], v149
	ds_read_b128 v[166:169], v149 offset:1024
	ds_read_b128 v[170:173], v149 offset:2048
	ds_read_b128 v[174:177], v149 offset:3072
	s_add_u32 s64, s64, 0x100000
	s_addc_u32 s65, s65, 0
	s_add_i32 m0, s9, 0xc000
	ds_read_b128 v[178:181], v148
	ds_read_b128 v[182:185], v148 offset:1024
	ds_read_b128 v[186:189], v148 offset:2048
	ds_read_b128 v[190:193], v148 offset:3072
	ds_read_b128 v[194:197], v148 offset:4096
	ds_read_b128 v[198:201], v148 offset:5120
	ds_read_b128 v[202:205], v148 offset:6144
	ds_read_b128 v[206:209], v148 offset:7168
	global_load_lds_dwordx4 v134, s[64:65]
	s_add_i32 m0, s9, 0xe000
	s_nop 0
	global_load_lds_dwordx4 v130, s[64:65]
	s_waitcnt vmcnt(8)
	s_waitcnt lgkmcnt(0)
	s_setprio 1
	s_barrier
	v_mfma_f32_16x16x32_bf16 v[124:127], v[140:143], v[178:181], v[124:127]
	v_mfma_f32_16x16x32_bf16 v[120:123], v[154:157], v[178:181], v[120:123]
	v_mfma_f32_16x16x32_bf16 v[116:119], v[140:143], v[186:189], v[116:119]
	v_mfma_f32_16x16x32_bf16 v[112:115], v[154:157], v[186:189], v[112:115]
	v_mfma_f32_16x16x32_bf16 v[108:111], v[140:143], v[194:197], v[108:111]
	v_mfma_f32_16x16x32_bf16 v[104:107], v[154:157], v[194:197], v[104:107]
	v_mfma_f32_16x16x32_bf16 v[100:103], v[140:143], v[202:205], v[100:103]
	v_mfma_f32_16x16x32_bf16 v[96:99], v[154:157], v[202:205], v[96:99]
	v_mfma_f32_16x16x32_bf16 v[124:127], v[150:153], v[182:185], v[124:127]
	v_mfma_f32_16x16x32_bf16 v[120:123], v[158:161], v[182:185], v[120:123]
	v_mfma_f32_16x16x32_bf16 v[116:119], v[150:153], v[190:193], v[116:119]
	v_mfma_f32_16x16x32_bf16 v[112:115], v[158:161], v[190:193], v[112:115]
	v_mfma_f32_16x16x32_bf16 v[108:111], v[150:153], v[198:201], v[108:111]
	v_mfma_f32_16x16x32_bf16 v[104:107], v[158:161], v[198:201], v[104:107]
	v_mfma_f32_16x16x32_bf16 v[100:103], v[150:153], v[206:209], v[100:103]
	v_mfma_f32_16x16x32_bf16 v[96:99], v[158:161], v[206:209], v[96:99]
	v_mfma_f32_16x16x32_bf16 v[92:95], v[162:165], v[178:181], v[92:95]
	v_mfma_f32_16x16x32_bf16 v[88:91], v[170:173], v[178:181], v[88:91]
	v_mfma_f32_16x16x32_bf16 v[84:87], v[162:165], v[186:189], v[84:87]
	v_mfma_f32_16x16x32_bf16 v[80:83], v[170:173], v[186:189], v[80:83]
	v_mfma_f32_16x16x32_bf16 v[76:79], v[162:165], v[194:197], v[76:79]
	v_mfma_f32_16x16x32_bf16 v[72:75], v[170:173], v[194:197], v[72:75]
	v_mfma_f32_16x16x32_bf16 v[68:71], v[162:165], v[202:205], v[68:71]
	v_mfma_f32_16x16x32_bf16 v[64:67], v[170:173], v[202:205], v[64:67]
	v_mfma_f32_16x16x32_bf16 v[92:95], v[166:169], v[182:185], v[92:95]
	v_mfma_f32_16x16x32_bf16 v[88:91], v[174:177], v[182:185], v[88:91]
	v_mfma_f32_16x16x32_bf16 v[84:87], v[166:169], v[190:193], v[84:87]
	v_mfma_f32_16x16x32_bf16 v[80:83], v[174:177], v[190:193], v[80:83]
	v_mfma_f32_16x16x32_bf16 v[76:79], v[166:169], v[198:201], v[76:79]
	v_mfma_f32_16x16x32_bf16 v[72:75], v[174:177], v[198:201], v[72:75]
	v_mfma_f32_16x16x32_bf16 v[68:71], v[166:169], v[206:209], v[68:71]
	v_mfma_f32_16x16x32_bf16 v[64:67], v[174:177], v[206:209], v[64:67]
	s_barrier
	s_setprio 0
	s_add_i32 s25, s59, s48
	s_mov_b32 m0, s25
	ds_read_b128 v[178:181], v148 offset:16384
	ds_read_b128 v[182:185], v148 offset:17408
	ds_read_b128 v[186:189], v148 offset:18432
	ds_read_b128 v[190:193], v148 offset:19456
	ds_read_b128 v[194:197], v148 offset:20480
	ds_read_b128 v[198:201], v148 offset:21504
	ds_read_b128 v[202:205], v148 offset:22528
	ds_read_b128 v[206:209], v148 offset:23552
	global_load_lds_dwordx4 v132, s[52:53]
	s_add_i32 m0, s25, 0x2000
	s_nop 0
	global_load_lds_dwordx4 v128, s[52:53]
	s_add_u32 s52, s52, 0x100000
	s_addc_u32 s53, s53, 0
	s_add_i32 s25, s60, s48
	s_mov_b32 m0, s25
	s_nop 0
	global_load_lds_dwordx4 v132, s[52:53]
	s_add_i32 m0, s25, 0x2000
	s_nop 0
	global_load_lds_dwordx4 v128, s[52:53]
	s_mov_b32 m0, s9
	s_nop 0
	global_load_lds_dwordx4 v134, s[44:45]
	s_mov_b32 m0, s50
	s_nop 0
	global_load_lds_dwordx4 v130, s[44:45]
	s_waitcnt vmcnt(8)
	s_waitcnt lgkmcnt(0)
	s_setprio 1
	s_barrier
	v_mfma_f32_16x16x32_bf16 v[60:63], v[140:143], v[178:181], v[60:63]
	v_mfma_f32_16x16x32_bf16 v[56:59], v[154:157], v[178:181], v[56:59]
	v_mfma_f32_16x16x32_bf16 v[52:55], v[140:143], v[186:189], v[52:55]
	v_mfma_f32_16x16x32_bf16 v[48:51], v[154:157], v[186:189], v[48:51]
	v_mfma_f32_16x16x32_bf16 v[44:47], v[140:143], v[194:197], v[44:47]
	v_mfma_f32_16x16x32_bf16 v[40:43], v[154:157], v[194:197], v[40:43]
	v_mfma_f32_16x16x32_bf16 v[36:39], v[140:143], v[202:205], v[36:39]
	v_mfma_f32_16x16x32_bf16 v[32:35], v[154:157], v[202:205], v[32:35]
	v_mfma_f32_16x16x32_bf16 v[60:63], v[150:153], v[182:185], v[60:63]
	v_mfma_f32_16x16x32_bf16 v[56:59], v[158:161], v[182:185], v[56:59]
	v_mfma_f32_16x16x32_bf16 v[52:55], v[150:153], v[190:193], v[52:55]
	v_mfma_f32_16x16x32_bf16 v[48:51], v[158:161], v[190:193], v[48:51]
	v_mfma_f32_16x16x32_bf16 v[44:47], v[150:153], v[198:201], v[44:47]
	v_mfma_f32_16x16x32_bf16 v[40:43], v[158:161], v[198:201], v[40:43]
	v_mfma_f32_16x16x32_bf16 v[36:39], v[150:153], v[206:209], v[36:39]
	v_mfma_f32_16x16x32_bf16 v[32:35], v[158:161], v[206:209], v[32:35]
	v_mfma_f32_16x16x32_bf16 v[28:31], v[162:165], v[178:181], v[28:31]
	v_mfma_f32_16x16x32_bf16 v[24:27], v[170:173], v[178:181], v[24:27]
	v_mfma_f32_16x16x32_bf16 v[20:23], v[162:165], v[186:189], v[20:23]
	v_mfma_f32_16x16x32_bf16 v[16:19], v[170:173], v[186:189], v[16:19]
	v_mfma_f32_16x16x32_bf16 v[12:15], v[162:165], v[194:197], v[12:15]
	v_mfma_f32_16x16x32_bf16 v[8:11], v[170:173], v[194:197], v[8:11]
	v_mfma_f32_16x16x32_bf16 v[4:7], v[162:165], v[202:205], v[4:7]
	v_mfma_f32_16x16x32_bf16 v[0:3], v[170:173], v[202:205], v[0:3]
	v_mfma_f32_16x16x32_bf16 v[28:31], v[166:169], v[182:185], v[28:31]
	v_mfma_f32_16x16x32_bf16 v[24:27], v[174:177], v[182:185], v[24:27]
	v_mfma_f32_16x16x32_bf16 v[20:23], v[166:169], v[190:193], v[20:23]
	v_mfma_f32_16x16x32_bf16 v[16:19], v[174:177], v[190:193], v[16:19]
	v_mfma_f32_16x16x32_bf16 v[12:15], v[166:169], v[198:201], v[12:15]
	v_mfma_f32_16x16x32_bf16 v[8:11], v[174:177], v[198:201], v[8:11]
	v_mfma_f32_16x16x32_bf16 v[4:7], v[166:169], v[206:209], v[4:7]
	v_mfma_f32_16x16x32_bf16 v[0:3], v[174:177], v[206:209], v[0:3]
	s_barrier
; #define PG8_STAGE(bufoff, gbase, voff) do { _Pragma("unroll") for (int _i = 0; _i < 2; ++_i) \
;         __builtin_amdgcn_global_load_lds((const unsigned*)((const char*)(gbase) + (voff)[_i]), (PG8_LAS unsigned*)(lds + (bufoff) + ldsw + _i * 8192), 16, 0, 0); } while (0)
; #define PG8_LDA(dst, b, h) do { _Pragma("unroll") for (int m = 0; m < 4; ++m) _Pragma("unroll") for (int k = 0; k < 2; ++k) dst[m][k] = *(const PG8_LAS bf16x8*)(lds + PG8_SA(b, h) + aoff + m * 2048 + k * 1024); } while (0)
; #define PG8_LDB(dst, b, h) do { _Pragma("unroll") for (int n = 0; n < 2; ++n) _Pragma("unroll") for (int k = 0; k < 2; ++k) dst[n][k] = *(const PG8_LAS bf16x8*)(lds + PG8_SB(b, h) + boff + n * 2048 + k * 1024); } while (0)
; #define PG8_WAIT_V(n) asm volatile("s_waitcnt vmcnt(" #n ")" ::: "memory")
; #define PG8_WAIT_L(n) asm volatile("s_waitcnt lgkmcnt(" #n ")" ::: "memory")
; #define PG8_BAR __builtin_amdgcn_s_barrier()
; #define PG8_SCHED __builtin_amdgcn_sched_barrier(0)
; template <class Epi, class Sched, bool ALIGN_EPI = false, bool SP2 = false, bool F8 = false>
; __device__ __forceinline__ void gemm_phase(PG8_LAS unsigned char* lds, const int K, const Sched& S, const Epi& E, const int wave) {
;     ...
;         for (int t = 0; t < nt; t += 2) {
;             const bool last = (t == nt - 2);
;             const char* a1 = cA + (size_t)(t + 1) * kstep;
;             const char* a2 = last ? nA : cA + (size_t)(t + 2) * kstep; const char* b2 = last ? nB : cB + (size_t)(t + 2) * kstep;
;             const char* a3 = a2 + kstep; const char* b3 = b2 + kstep;
;     ...
;             PG8_LDB(B0, 1, 0); PG8_LDB(B1, 1, 1); PG8_SCHED; PG8_LDA(At, 1, 0); PG8_STAGE(PG8_SA(0, 1), a2 + hstep, voffA);
;             PG8_WAIT_V(8); PG8_WAIT_L(0); PG8_BAR; PG8_MMA(0, 0, At, B0); PG8_MMA(0, 1, At, B1); PG8_BAR; PG8_SCHED;
;             PG8_LDA(At, 1, 1); PG8_STAGE(PG8_SB(1, 0), b3, voffB); PG8_STAGE(PG8_SB(1, 1), b3 + hstep, voffB); PG8_STAGE(PG8_SA(1, 0), a3, voffA);
;             PG8_WAIT_V(8); PG8_WAIT_L(0); PG8_BAR; PG8_MMA(1, 0, At, B0); PG8_MMA(1, 1, At, B1); PG8_BAR; PG8_SCHED;
.Lmid_k1240:
	s_setprio 0
	s_add_i32 s25, 0, 0x18000
	v_add_u32_e32 v149, s25, v146
	s_add_i32 s52, 0, 0x1c000
	ds_read_b128 v[140:143], v149
	ds_read_b128 v[150:153], v149 offset:1024
	ds_read_b128 v[154:157], v149 offset:2048
	ds_read_b128 v[158:161], v149 offset:3072
	v_add_u32_e32 v149, s52, v146
	ds_read_b128 v[162:165], v149
	ds_read_b128 v[166:169], v149 offset:1024
	ds_read_b128 v[170:173], v149 offset:2048
	ds_read_b128 v[174:177], v149 offset:3072
	s_add_u32 s44, s44, 0x100000
	s_addc_u32 s45, s45, 0
	s_mov_b32 m0, s51
	ds_read_b128 v[178:181], v148 offset:32768
	ds_read_b128 v[182:185], v148 offset:33792
	ds_read_b128 v[186:189], v148 offset:34816
	ds_read_b128 v[190:193], v148 offset:35840
	ds_read_b128 v[194:197], v148 offset:36864
	ds_read_b128 v[198:201], v148 offset:37888
	ds_read_b128 v[202:205], v148 offset:38912
	ds_read_b128 v[206:209], v148 offset:39936
	global_load_lds_dwordx4 v134, s[44:45]
	s_mov_b32 m0, s54
	s_nop 0
	global_load_lds_dwordx4 v130, s[44:45]
	s_waitcnt vmcnt(8)
	s_waitcnt lgkmcnt(0)
	s_setprio 1
	s_barrier
	v_mfma_f32_16x16x32_bf16 v[124:127], v[140:143], v[178:181], v[124:127]
	v_mfma_f32_16x16x32_bf16 v[120:123], v[154:157], v[178:181], v[120:123]
	v_mfma_f32_16x16x32_bf16 v[116:119], v[140:143], v[186:189], v[116:119]
	v_mfma_f32_16x16x32_bf16 v[112:115], v[154:157], v[186:189], v[112:115]
	v_mfma_f32_16x16x32_bf16 v[108:111], v[140:143], v[194:197], v[108:111]
	v_mfma_f32_16x16x32_bf16 v[104:107], v[154:157], v[194:197], v[104:107]
	v_mfma_f32_16x16x32_bf16 v[100:103], v[140:143], v[202:205], v[100:103]
	v_mfma_f32_16x16x32_bf16 v[96:99], v[154:157], v[202:205], v[96:99]
	v_mfma_f32_16x16x32_bf16 v[124:127], v[150:153], v[182:185], v[124:127]
	v_mfma_f32_16x16x32_bf16 v[120:123], v[158:161], v[182:185], v[120:123]
	v_mfma_f32_16x16x32_bf16 v[116:119], v[150:153], v[190:193], v[116:119]
	v_mfma_f32_16x16x32_bf16 v[112:115], v[158:161], v[190:193], v[112:115]
	v_mfma_f32_16x16x32_bf16 v[108:111], v[150:153], v[198:201], v[108:111]
	v_mfma_f32_16x16x32_bf16 v[104:107], v[158:161], v[198:201], v[104:107]
	v_mfma_f32_16x16x32_bf16 v[100:103], v[150:153], v[206:209], v[100:103]
	v_mfma_f32_16x16x32_bf16 v[96:99], v[158:161], v[206:209], v[96:99]
	v_mfma_f32_16x16x32_bf16 v[92:95], v[162:165], v[178:181], v[92:95]
	v_mfma_f32_16x16x32_bf16 v[88:91], v[170:173], v[178:181], v[88:91]
	v_mfma_f32_16x16x32_bf16 v[84:87], v[162:165], v[186:189], v[84:87]
	v_mfma_f32_16x16x32_bf16 v[80:83], v[170:173], v[186:189], v[80:83]
	v_mfma_f32_16x16x32_bf16 v[76:79], v[162:165], v[194:197], v[76:79]
	v_mfma_f32_16x16x32_bf16 v[72:75], v[170:173], v[194:197], v[72:75]
	v_mfma_f32_16x16x32_bf16 v[68:71], v[162:165], v[202:205], v[68:71]
	v_mfma_f32_16x16x32_bf16 v[64:67], v[170:173], v[202:205], v[64:67]
	v_mfma_f32_16x16x32_bf16 v[92:95], v[166:169], v[182:185], v[92:95]
	v_mfma_f32_16x16x32_bf16 v[88:91], v[174:177], v[182:185], v[88:91]
	v_mfma_f32_16x16x32_bf16 v[84:87], v[166:169], v[190:193], v[84:87]
	v_mfma_f32_16x16x32_bf16 v[80:83], v[174:177], v[190:193], v[80:83]
	v_mfma_f32_16x16x32_bf16 v[76:79], v[166:169], v[198:201], v[76:79]
	v_mfma_f32_16x16x32_bf16 v[72:75], v[174:177], v[198:201], v[72:75]
	v_mfma_f32_16x16x32_bf16 v[68:71], v[166:169], v[206:209], v[68:71]
	v_mfma_f32_16x16x32_bf16 v[64:67], v[174:177], v[206:209], v[64:67]
	s_barrier
	s_setprio 0
	s_add_i32 s25, s25, s48
	s_mov_b32 m0, s25
	ds_read_b128 v[178:181], v148 offset:49152
	ds_read_b128 v[182:185], v148 offset:50176
	ds_read_b128 v[186:189], v148 offset:51200
	ds_read_b128 v[190:193], v148 offset:52224
	ds_read_b128 v[194:197], v148 offset:53248
	ds_read_b128 v[198:201], v148 offset:54272
	ds_read_b128 v[202:205], v148 offset:55296
	ds_read_b128 v[206:209], v148 offset:56320
	global_load_lds_dwordx4 v132, s[42:43]
	s_add_i32 m0, s25, 0x2000
	s_nop 0
	global_load_lds_dwordx4 v128, s[42:43]
	s_add_u32 s42, s42, 0x100000
	s_addc_u32 s43, s43, 0
	s_add_i32 s25, s52, s48
	s_mov_b32 m0, s25
	s_nop 0
	global_load_lds_dwordx4 v132, s[42:43]
	s_add_i32 m0, s25, 0x2000
	s_nop 0
	global_load_lds_dwordx4 v128, s[42:43]
	s_mov_b32 m0, s55
	s_nop 0
	global_load_lds_dwordx4 v134, s[40:41]
	s_mov_b32 m0, s57
	s_nop 0
	global_load_lds_dwordx4 v130, s[40:41]
	s_waitcnt vmcnt(8)
	s_waitcnt lgkmcnt(0)
	s_setprio 1
	s_barrier
	v_mfma_f32_16x16x32_bf16 v[60:63], v[140:143], v[178:181], v[60:63]
	v_mfma_f32_16x16x32_bf16 v[56:59], v[154:157], v[178:181], v[56:59]
	v_mfma_f32_16x16x32_bf16 v[52:55], v[140:143], v[186:189], v[52:55]
	v_mfma_f32_16x16x32_bf16 v[48:51], v[154:157], v[186:189], v[48:51]
	v_mfma_f32_16x16x32_bf16 v[44:47], v[140:143], v[194:197], v[44:47]
	v_mfma_f32_16x16x32_bf16 v[40:43], v[154:157], v[194:197], v[40:43]
	v_mfma_f32_16x16x32_bf16 v[36:39], v[140:143], v[202:205], v[36:39]
	v_mfma_f32_16x16x32_bf16 v[32:35], v[154:157], v[202:205], v[32:35]
	v_mfma_f32_16x16x32_bf16 v[60:63], v[150:153], v[182:185], v[60:63]
	v_mfma_f32_16x16x32_bf16 v[56:59], v[158:161], v[182:185], v[56:59]
	v_mfma_f32_16x16x32_bf16 v[52:55], v[150:153], v[190:193], v[52:55]
	v_mfma_f32_16x16x32_bf16 v[48:51], v[158:161], v[190:193], v[48:51]
	v_mfma_f32_16x16x32_bf16 v[44:47], v[150:153], v[198:201], v[44:47]
	v_mfma_f32_16x16x32_bf16 v[40:43], v[158:161], v[198:201], v[40:43]
	v_mfma_f32_16x16x32_bf16 v[36:39], v[150:153], v[206:209], v[36:39]
	v_mfma_f32_16x16x32_bf16 v[32:35], v[158:161], v[206:209], v[32:35]
	v_mfma_f32_16x16x32_bf16 v[28:31], v[162:165], v[178:181], v[28:31]
	v_mfma_f32_16x16x32_bf16 v[24:27], v[170:173], v[178:181], v[24:27]
	v_mfma_f32_16x16x32_bf16 v[20:23], v[162:165], v[186:189], v[20:23]
	v_mfma_f32_16x16x32_bf16 v[16:19], v[170:173], v[186:189], v[16:19]
	v_mfma_f32_16x16x32_bf16 v[12:15], v[162:165], v[194:197], v[12:15]
	v_mfma_f32_16x16x32_bf16 v[8:11], v[170:173], v[194:197], v[8:11]
	v_mfma_f32_16x16x32_bf16 v[4:7], v[162:165], v[202:205], v[4:7]
	v_mfma_f32_16x16x32_bf16 v[0:3], v[170:173], v[202:205], v[0:3]
	v_mfma_f32_16x16x32_bf16 v[28:31], v[166:169], v[182:185], v[28:31]
	v_mfma_f32_16x16x32_bf16 v[24:27], v[174:177], v[182:185], v[24:27]
	v_mfma_f32_16x16x32_bf16 v[20:23], v[166:169], v[190:193], v[20:23]
	v_mfma_f32_16x16x32_bf16 v[16:19], v[174:177], v[190:193], v[16:19]
	v_mfma_f32_16x16x32_bf16 v[12:15], v[166:169], v[198:201], v[12:15]
	v_mfma_f32_16x16x32_bf16 v[8:11], v[174:177], v[198:201], v[8:11]
	v_mfma_f32_16x16x32_bf16 v[4:7], v[166:169], v[206:209], v[4:7]
	v_mfma_f32_16x16x32_bf16 v[0:3], v[174:177], v[206:209], v[0:3]
	s_barrier
	s_setprio 0
	s_add_i32 s23, s23, 2
	s_add_u32 s38, s38, 0x100
	s_addc_u32 s39, s39, 0
	s_cmp_gt_u32 s23, 61
	s_cbranch_scc0 .LBB0_1240
	s_and_b64 vcc, exec, s[18:19]
	s_cbranch_vccz .LBB0_1243
	s_barrier

; #define PG8_STAGE(bufoff, gbase, voff) do { _Pragma("unroll") for (int _i = 0; _i < 2; ++_i) \
;         __builtin_amdgcn_global_load_lds((const unsigned*)((const char*)(gbase) + (voff)[_i]), (PG8_LAS unsigned*)(lds + (bufoff) + ldsw + _i * 8192), 16, 0, 0); } while (0)
; #define PG8_LDA(dst, b, h) do { _Pragma("unroll") for (int m = 0; m < 4; ++m) _Pragma("unroll") for (int k = 0; k < 2; ++k) dst[m][k] = *(const PG8_LAS bf16x8*)(lds + PG8_SA(b, h) + aoff + m * 2048 + k * 1024); } while (0)
; #define PG8_LDB(dst, b, h) do { _Pragma("unroll") for (int n = 0; n < 2; ++n) _Pragma("unroll") for (int k = 0; k < 2; ++k) dst[n][k] = *(const PG8_LAS bf16x8*)(lds + PG8_SB(b, h) + boff + n * 2048 + k * 1024); } while (0)
; #define PG8_WAIT_V(n) asm volatile("s_waitcnt vmcnt(" #n ")" ::: "memory")
; #define PG8_WAIT_L(n) asm volatile("s_waitcnt lgkmcnt(" #n ")" ::: "memory")
; #define PG8_BAR __builtin_amdgcn_s_barrier()
; template <class Epi, class Sched, bool ALIGN_EPI = false, bool SP2 = false, bool F8 = false>
; __device__ __forceinline__ void gemm_phase(PG8_LAS unsigned char* lds, const int K, const Sched& S, const Epi& E, const int wave) {
;     ...
;             const bool last = (t == nt - 2);
;             const char* a1 = cA + (size_t)(t + 1) * kstep;
;             const char* a2 = last ? nA : cA + (size_t)(t + 2) * kstep; const char* b2 = last ? nB : cB + (size_t)(t + 2) * kstep;
;             const char* a3 = a2 + kstep; const char* b3 = b2 + kstep;
;             asm volatile("" : "+s"(a1), "+s"(a2), "+s"(b2), "+s"(a3), "+s"(b3));
;             if (last && has_next) S.a_ready(nxt);
;             if constexpr (Epi::KHOOK) { if (cur.prob == 2 ? (t == 16) : (t == 32 || t == 48)) { if (wr == 0) PG8_BAR;
;                 E.khook(acc, cur, (cur.prob == 2 || t == 48) ? 1 : 0, wr, wc, fr, fq); if (wr == 1) PG8_BAR; } }
;             if constexpr (SP2) {
;             PG8_LDB(B0, 0, 0); PG8_LDB(B1, 0, 1); PG8_SCHED; PG8_LDA(At, 0, 0); PG8_STAGE(PG8_SA(1, 1), a1 + hstep, voffA);
;             PG8_WAIT_V(8); PG8_WAIT_L(0); PG8_BAR; PG8_MMA(0, 0, At, B0); PG8_MMA(0, 1, At, B1); PG8_BAR; PG8_SCHED;
;             PG8_LDA(At, 0, 1); PG8_STAGE(PG8_SB(0, 0), b2, voffB); PG8_STAGE(PG8_SB(0, 1), b2 + hstep, voffB); PG8_STAGE(PG8_SA(0, 0), a2, voffA);
;             PG8_WAIT_V(8); PG8_WAIT_L(0); PG8_BAR; PG8_MMA(1, 0, At, B0); PG8_MMA(1, 1, At, B1); PG8_BAR; PG8_SCHED;
.Lpeel_k1348:
	s_add_i32 s87, s8, 2
	s_cmp_eq_u32 s82, s8
	s_cselect_b32 s40, s79, s83
	s_cselect_b32 s41, s78, s84
	s_cselect_b32 s43, s80, s86
	s_cselect_b32 s42, s81, s85
	s_add_u32 s8, s40, 0x80
	s_addc_u32 s9, s41, 0
	s_add_u32 s38, s42, 0x80
	s_addc_u32 s39, s43, 0
	s_mov_b64 s[88:89], s[6:7]
	v_add_u32_e32 v1, s67, v166
	ds_read_b128 v[132:135], v1
	ds_read_b128 v[136:139], v1 offset:1024
	ds_read_b128 v[156:159], v1 offset:2048
	ds_read_b128 v[160:163], v1 offset:3072
	v_add_u32_e32 v1, s72, v166
	ds_read_b128 v[170:173], v1
	ds_read_b128 v[174:177], v1 offset:1024
	ds_read_b128 v[178:181], v1 offset:2048
	ds_read_b128 v[182:185], v1 offset:3072
	s_add_u32 s88, s88, 0x2b0000
	s_addc_u32 s89, s89, 0
	s_add_i32 m0, s58, 0xc000
	ds_read_b128 v[186:189], v168
	ds_read_b128 v[190:193], v168 offset:1024
	ds_read_b128 v[194:197], v168 offset:2048
	ds_read_b128 v[198:201], v168 offset:3072
	ds_read_b128 v[202:205], v168 offset:4096
	ds_read_b128 v[206:209], v168 offset:5120
	ds_read_b128 v[210:213], v168 offset:6144
	ds_read_b128 v[214:217], v168 offset:7168
	global_load_lds_dwordx4 v140, s[88:89]
	s_add_i32 m0, s58, 0xe000
	s_nop 0
	global_load_lds_dwordx4 v144, s[88:89]
	s_waitcnt vmcnt(8)
	s_waitcnt lgkmcnt(0)
	s_setprio 1
	s_barrier
	v_mfma_f32_16x16x32_bf16 v[128:131], v[132:135], v[186:189], 0
	v_mfma_f32_16x16x32_bf16 v[124:127], v[156:159], v[186:189], 0
	v_mfma_f32_16x16x32_bf16 v[120:123], v[132:135], v[194:197], 0
	v_mfma_f32_16x16x32_bf16 v[116:119], v[156:159], v[194:197], 0
	v_mfma_f32_16x16x32_bf16 v[112:115], v[132:135], v[202:205], 0
	v_mfma_f32_16x16x32_bf16 v[108:111], v[156:159], v[202:205], 0
	v_mfma_f32_16x16x32_bf16 v[104:107], v[132:135], v[210:213], 0
	v_mfma_f32_16x16x32_bf16 v[100:103], v[156:159], v[210:213], 0
	v_mfma_f32_16x16x32_bf16 v[128:131], v[136:139], v[190:193], v[128:131]
	v_mfma_f32_16x16x32_bf16 v[124:127], v[160:163], v[190:193], v[124:127]
	v_mfma_f32_16x16x32_bf16 v[120:123], v[136:139], v[198:201], v[120:123]
	v_mfma_f32_16x16x32_bf16 v[116:119], v[160:163], v[198:201], v[116:119]
	v_mfma_f32_16x16x32_bf16 v[112:115], v[136:139], v[206:209], v[112:115]
	v_mfma_f32_16x16x32_bf16 v[108:111], v[160:163], v[206:209], v[108:111]
	v_mfma_f32_16x16x32_bf16 v[104:107], v[136:139], v[214:217], v[104:107]
	v_mfma_f32_16x16x32_bf16 v[100:103], v[160:163], v[214:217], v[100:103]
	v_mfma_f32_16x16x32_bf16 v[96:99], v[170:173], v[186:189], 0
	v_mfma_f32_16x16x32_bf16 v[92:95], v[178:181], v[186:189], 0
	v_mfma_f32_16x16x32_bf16 v[88:91], v[170:173], v[194:197], 0
	v_mfma_f32_16x16x32_bf16 v[84:87], v[178:181], v[194:197], 0
	v_mfma_f32_16x16x32_bf16 v[80:83], v[170:173], v[202:205], 0
	v_mfma_f32_16x16x32_bf16 v[76:79], v[178:181], v[202:205], 0
	v_mfma_f32_16x16x32_bf16 v[72:75], v[170:173], v[210:213], 0
	v_mfma_f32_16x16x32_bf16 v[68:71], v[178:181], v[210:213], 0
	v_mfma_f32_16x16x32_bf16 v[96:99], v[174:177], v[190:193], v[96:99]
	v_mfma_f32_16x16x32_bf16 v[92:95], v[182:185], v[190:193], v[92:95]
	v_mfma_f32_16x16x32_bf16 v[88:91], v[174:177], v[198:201], v[88:91]
	v_mfma_f32_16x16x32_bf16 v[84:87], v[182:185], v[198:201], v[84:87]
	v_mfma_f32_16x16x32_bf16 v[80:83], v[174:177], v[206:209], v[80:83]
	v_mfma_f32_16x16x32_bf16 v[76:79], v[182:185], v[206:209], v[76:79]
	v_mfma_f32_16x16x32_bf16 v[72:75], v[174:177], v[214:217], v[72:75]
	v_mfma_f32_16x16x32_bf16 v[68:71], v[182:185], v[214:217], v[68:71]
	s_barrier
	s_setprio 0
	s_add_i32 s88, s67, s57
	s_mov_b32 m0, s88
	ds_read_b128 v[186:189], v168 offset:16384
	ds_read_b128 v[190:193], v168 offset:17408
	ds_read_b128 v[194:197], v168 offset:18432
	ds_read_b128 v[198:201], v168 offset:19456
	ds_read_b128 v[202:205], v168 offset:20480
	ds_read_b128 v[206:209], v168 offset:21504
	ds_read_b128 v[210:213], v168 offset:22528
	ds_read_b128 v[214:217], v168 offset:23552
	global_load_lds_dwordx4 v142, s[42:43]
	s_add_i32 m0, s88, 0x2000
	s_nop 0
	global_load_lds_dwordx4 v146, s[42:43]
	s_add_u32 s42, s42, 0x2b0000
	s_addc_u32 s43, s43, 0
	s_add_i32 s88, s72, s57
	s_mov_b32 m0, s88
	s_nop 0
	global_load_lds_dwordx4 v142, s[42:43]
	s_add_i32 m0, s88, 0x2000
	s_nop 0
	global_load_lds_dwordx4 v146, s[42:43]
	s_mov_b32 m0, s58
	s_nop 0
	global_load_lds_dwordx4 v140, s[40:41]
	s_mov_b32 m0, s59
	s_nop 0
	global_load_lds_dwordx4 v144, s[40:41]
	s_waitcnt vmcnt(8)
	s_waitcnt lgkmcnt(0)
	s_setprio 1
	s_barrier
	v_mfma_f32_16x16x32_bf16 v[64:67], v[132:135], v[186:189], 0
	v_mfma_f32_16x16x32_bf16 v[60:63], v[156:159], v[186:189], 0
	v_mfma_f32_16x16x32_bf16 v[56:59], v[132:135], v[194:197], 0
	v_mfma_f32_16x16x32_bf16 v[52:55], v[156:159], v[194:197], 0
	v_mfma_f32_16x16x32_bf16 v[48:51], v[132:135], v[202:205], 0
	v_mfma_f32_16x16x32_bf16 v[44:47], v[156:159], v[202:205], 0
	v_mfma_f32_16x16x32_bf16 v[40:43], v[132:135], v[210:213], 0
	v_mfma_f32_16x16x32_bf16 v[36:39], v[156:159], v[210:213], 0
	v_mfma_f32_16x16x32_bf16 v[64:67], v[136:139], v[190:193], v[64:67]
	v_mfma_f32_16x16x32_bf16 v[60:63], v[160:163], v[190:193], v[60:63]
	v_mfma_f32_16x16x32_bf16 v[56:59], v[136:139], v[198:201], v[56:59]
	v_mfma_f32_16x16x32_bf16 v[52:55], v[160:163], v[198:201], v[52:55]
	v_mfma_f32_16x16x32_bf16 v[48:51], v[136:139], v[206:209], v[48:51]
	v_mfma_f32_16x16x32_bf16 v[44:47], v[160:163], v[206:209], v[44:47]
	v_mfma_f32_16x16x32_bf16 v[40:43], v[136:139], v[214:217], v[40:43]
	v_mfma_f32_16x16x32_bf16 v[36:39], v[160:163], v[214:217], v[36:39]
	v_mfma_f32_16x16x32_bf16 v[32:35], v[170:173], v[186:189], 0
	v_mfma_f32_16x16x32_bf16 v[28:31], v[178:181], v[186:189], 0
	v_mfma_f32_16x16x32_bf16 v[24:27], v[170:173], v[194:197], 0
	v_mfma_f32_16x16x32_bf16 v[20:23], v[178:181], v[194:197], 0
	v_mfma_f32_16x16x32_bf16 v[16:19], v[170:173], v[202:205], 0
	v_mfma_f32_16x16x32_bf16 v[12:15], v[178:181], v[202:205], 0
	v_mfma_f32_16x16x32_bf16 v[8:11], v[170:173], v[210:213], 0
	v_mfma_f32_16x16x32_bf16 v[2:5], v[178:181], v[210:213], 0
	v_mfma_f32_16x16x32_bf16 v[32:35], v[174:177], v[190:193], v[32:35]
	v_mfma_f32_16x16x32_bf16 v[28:31], v[182:185], v[190:193], v[28:31]
	v_mfma_f32_16x16x32_bf16 v[24:27], v[174:177], v[198:201], v[24:27]
	v_mfma_f32_16x16x32_bf16 v[20:23], v[182:185], v[198:201], v[20:23]
	v_mfma_f32_16x16x32_bf16 v[16:19], v[174:177], v[206:209], v[16:19]
	v_mfma_f32_16x16x32_bf16 v[12:15], v[182:185], v[206:209], v[12:15]
	v_mfma_f32_16x16x32_bf16 v[8:11], v[174:177], v[214:217], v[8:11]
	v_mfma_f32_16x16x32_bf16 v[2:5], v[182:185], v[214:217], v[2:5]
	s_barrier
	s_branch .Lmid_k1348
; #define PG8_STAGE(bufoff, gbase, voff) do { _Pragma("unroll") for (int _i = 0; _i < 2; ++_i) \
;         __builtin_amdgcn_global_load_lds((const unsigned*)((const char*)(gbase) + (voff)[_i]), (PG8_LAS unsigned*)(lds + (bufoff) + ldsw + _i * 8192), 16, 0, 0); } while (0)
; #define PG8_LDA(dst, b, h) do { _Pragma("unroll") for (int m = 0; m < 4; ++m) _Pragma("unroll") for (int k = 0; k < 2; ++k) dst[m][k] = *(const PG8_LAS bf16x8*)(lds + PG8_SA(b, h) + aoff + m * 2048 + k * 1024); } while (0)
; #define PG8_LDB(dst, b, h) do { _Pragma("unroll") for (int n = 0; n < 2; ++n) _Pragma("unroll") for (int k = 0; k < 2; ++k) dst[n][k] = *(const PG8_LAS bf16x8*)(lds + PG8_SB(b, h) + boff + n * 2048 + k * 1024); } while (0)
; #define PG8_WAIT_V(n) asm volatile("s_waitcnt vmcnt(" #n ")" ::: "memory")
; #define PG8_WAIT_L(n) asm volatile("s_waitcnt lgkmcnt(" #n ")" ::: "memory")
; #define PG8_BAR __builtin_amdgcn_s_barrier()
; template <class Epi, class Sched, bool ALIGN_EPI = false, bool SP2 = false, bool F8 = false>
; __device__ __forceinline__ void gemm_phase(PG8_LAS unsigned char* lds, const int K, const Sched& S, const Epi& E, const int wave) {
;     ...
;             const bool last = (t == nt - 2);
;             const char* a1 = cA + (size_t)(t + 1) * kstep;
;             const char* a2 = last ? nA : cA + (size_t)(t + 2) * kstep; const char* b2 = last ? nB : cB + (size_t)(t + 2) * kstep;
;             const char* a3 = a2 + kstep; const char* b3 = b2 + kstep;
;             asm volatile("" : "+s"(a1), "+s"(a2), "+s"(b2), "+s"(a3), "+s"(b3));
;             if (last && has_next) S.a_ready(nxt);
;             if constexpr (Epi::KHOOK) { if (cur.prob == 2 ? (t == 16) : (t == 32 || t == 48)) { if (wr == 0) PG8_BAR;
;                 E.khook(acc, cur, (cur.prob == 2 || t == 48) ? 1 : 0, wr, wc, fr, fq); if (wr == 1) PG8_BAR; } }
;             if constexpr (SP2) {
;             PG8_LDB(B0, 0, 0); PG8_LDB(B1, 0, 1); PG8_SCHED; PG8_LDA(At, 0, 0); PG8_STAGE(PG8_SA(1, 1), a1 + hstep, voffA);
;             PG8_WAIT_V(8); PG8_WAIT_L(0); PG8_BAR; PG8_MMA(0, 0, At, B0); PG8_MMA(0, 1, At, B1); PG8_BAR; PG8_SCHED;
;             PG8_LDA(At, 0, 1); PG8_STAGE(PG8_SB(0, 0), b2, voffB); PG8_STAGE(PG8_SB(0, 1), b2 + hstep, voffB); PG8_STAGE(PG8_SA(0, 0), a2, voffA);
;             PG8_WAIT_V(8); PG8_WAIT_L(0); PG8_BAR; PG8_MMA(1, 0, At, B0); PG8_MMA(1, 1, At, B1); PG8_BAR; PG8_SCHED;
.LBB0_1348:
	s_add_i32 s87, s8, 2
	s_cmp_eq_u32 s82, s8
	s_cselect_b32 s40, s79, s83
	s_cselect_b32 s41, s78, s84
	s_cselect_b32 s43, s80, s86
	s_cselect_b32 s42, s81, s85
	s_add_u32 s8, s40, 0x80
	s_addc_u32 s9, s41, 0
	s_add_u32 s38, s42, 0x80
	s_addc_u32 s39, s43, 0
	s_mov_b64 s[88:89], s[6:7]
	v_add_u32_e32 v1, s67, v166
	ds_read_b128 v[132:135], v1
	ds_read_b128 v[136:139], v1 offset:1024
	ds_read_b128 v[156:159], v1 offset:2048
	ds_read_b128 v[160:163], v1 offset:3072
	v_add_u32_e32 v1, s72, v166
	ds_read_b128 v[170:173], v1
	ds_read_b128 v[174:177], v1 offset:1024
	ds_read_b128 v[178:181], v1 offset:2048
	ds_read_b128 v[182:185], v1 offset:3072
	s_add_u32 s88, s88, 0x2b0000
	s_addc_u32 s89, s89, 0
	s_add_i32 m0, s58, 0xc000
	ds_read_b128 v[186:189], v168
	ds_read_b128 v[190:193], v168 offset:1024
	ds_read_b128 v[194:197], v168 offset:2048
	ds_read_b128 v[198:201], v168 offset:3072
	ds_read_b128 v[202:205], v168 offset:4096
	ds_read_b128 v[206:209], v168 offset:5120
	ds_read_b128 v[210:213], v168 offset:6144
	ds_read_b128 v[214:217], v168 offset:7168
	global_load_lds_dwordx4 v140, s[88:89]
	s_add_i32 m0, s58, 0xe000
	s_nop 0
	global_load_lds_dwordx4 v144, s[88:89]
	s_waitcnt vmcnt(8)
	s_waitcnt lgkmcnt(0)
	s_setprio 1
	s_barrier
	v_mfma_f32_16x16x32_bf16 v[128:131], v[132:135], v[186:189], v[128:131]
	v_mfma_f32_16x16x32_bf16 v[124:127], v[156:159], v[186:189], v[124:127]
	v_mfma_f32_16x16x32_bf16 v[120:123], v[132:135], v[194:197], v[120:123]
	v_mfma_f32_16x16x32_bf16 v[116:119], v[156:159], v[194:197], v[116:119]
	v_mfma_f32_16x16x32_bf16 v[112:115], v[132:135], v[202:205], v[112:115]
	v_mfma_f32_16x16x32_bf16 v[108:111], v[156:159], v[202:205], v[108:111]
	v_mfma_f32_16x16x32_bf16 v[104:107], v[132:135], v[210:213], v[104:107]
	v_mfma_f32_16x16x32_bf16 v[100:103], v[156:159], v[210:213], v[100:103]
	v_mfma_f32_16x16x32_bf16 v[128:131], v[136:139], v[190:193], v[128:131]
	v_mfma_f32_16x16x32_bf16 v[124:127], v[160:163], v[190:193], v[124:127]
	v_mfma_f32_16x16x32_bf16 v[120:123], v[136:139], v[198:201], v[120:123]
	v_mfma_f32_16x16x32_bf16 v[116:119], v[160:163], v[198:201], v[116:119]
	v_mfma_f32_16x16x32_bf16 v[112:115], v[136:139], v[206:209], v[112:115]
	v_mfma_f32_16x16x32_bf16 v[108:111], v[160:163], v[206:209], v[108:111]
	v_mfma_f32_16x16x32_bf16 v[104:107], v[136:139], v[214:217], v[104:107]
	v_mfma_f32_16x16x32_bf16 v[100:103], v[160:163], v[214:217], v[100:103]
	v_mfma_f32_16x16x32_bf16 v[96:99], v[170:173], v[186:189], v[96:99]
	v_mfma_f32_16x16x32_bf16 v[92:95], v[178:181], v[186:189], v[92:95]
	v_mfma_f32_16x16x32_bf16 v[88:91], v[170:173], v[194:197], v[88:91]
	v_mfma_f32_16x16x32_bf16 v[84:87], v[178:181], v[194:197], v[84:87]
	v_mfma_f32_16x16x32_bf16 v[80:83], v[170:173], v[202:205], v[80:83]
	v_mfma_f32_16x16x32_bf16 v[76:79], v[178:181], v[202:205], v[76:79]
	v_mfma_f32_16x16x32_bf16 v[72:75], v[170:173], v[210:213], v[72:75]
	v_mfma_f32_16x16x32_bf16 v[68:71], v[178:181], v[210:213], v[68:71]
	v_mfma_f32_16x16x32_bf16 v[96:99], v[174:177], v[190:193], v[96:99]
	v_mfma_f32_16x16x32_bf16 v[92:95], v[182:185], v[190:193], v[92:95]
	v_mfma_f32_16x16x32_bf16 v[88:91], v[174:177], v[198:201], v[88:91]
	v_mfma_f32_16x16x32_bf16 v[84:87], v[182:185], v[198:201], v[84:87]
	v_mfma_f32_16x16x32_bf16 v[80:83], v[174:177], v[206:209], v[80:83]
	v_mfma_f32_16x16x32_bf16 v[76:79], v[182:185], v[206:209], v[76:79]
	v_mfma_f32_16x16x32_bf16 v[72:75], v[174:177], v[214:217], v[72:75]
	v_mfma_f32_16x16x32_bf16 v[68:71], v[182:185], v[214:217], v[68:71]
	s_barrier
	s_setprio 0
	s_add_i32 s88, s67, s57
	s_mov_b32 m0, s88
	ds_read_b128 v[186:189], v168 offset:16384
	ds_read_b128 v[190:193], v168 offset:17408
	ds_read_b128 v[194:197], v168 offset:18432
	ds_read_b128 v[198:201], v168 offset:19456
	ds_read_b128 v[202:205], v168 offset:20480
	ds_read_b128 v[206:209], v168 offset:21504
	ds_read_b128 v[210:213], v168 offset:22528
	ds_read_b128 v[214:217], v168 offset:23552
	global_load_lds_dwordx4 v142, s[42:43]
	s_add_i32 m0, s88, 0x2000
	s_nop 0
	global_load_lds_dwordx4 v146, s[42:43]
	s_add_u32 s42, s42, 0x2b0000
	s_addc_u32 s43, s43, 0
	s_add_i32 s88, s72, s57
	s_mov_b32 m0, s88
	s_nop 0
	global_load_lds_dwordx4 v142, s[42:43]
	s_add_i32 m0, s88, 0x2000
	s_nop 0
	global_load_lds_dwordx4 v146, s[42:43]
	s_mov_b32 m0, s58
	s_nop 0
	global_load_lds_dwordx4 v140, s[40:41]
	s_mov_b32 m0, s59
	s_nop 0
	global_load_lds_dwordx4 v144, s[40:41]
	s_waitcnt vmcnt(8)
	s_waitcnt lgkmcnt(0)
	s_setprio 1
	s_barrier
	v_mfma_f32_16x16x32_bf16 v[64:67], v[132:135], v[186:189], v[64:67]
	v_mfma_f32_16x16x32_bf16 v[60:63], v[156:159], v[186:189], v[60:63]
	v_mfma_f32_16x16x32_bf16 v[56:59], v[132:135], v[194:197], v[56:59]
	v_mfma_f32_16x16x32_bf16 v[52:55], v[156:159], v[194:197], v[52:55]
	v_mfma_f32_16x16x32_bf16 v[48:51], v[132:135], v[202:205], v[48:51]
	v_mfma_f32_16x16x32_bf16 v[44:47], v[156:159], v[202:205], v[44:47]
	v_mfma_f32_16x16x32_bf16 v[40:43], v[132:135], v[210:213], v[40:43]
	v_mfma_f32_16x16x32_bf16 v[36:39], v[156:159], v[210:213], v[36:39]
	v_mfma_f32_16x16x32_bf16 v[64:67], v[136:139], v[190:193], v[64:67]
	v_mfma_f32_16x16x32_bf16 v[60:63], v[160:163], v[190:193], v[60:63]
	v_mfma_f32_16x16x32_bf16 v[56:59], v[136:139], v[198:201], v[56:59]
	v_mfma_f32_16x16x32_bf16 v[52:55], v[160:163], v[198:201], v[52:55]
	v_mfma_f32_16x16x32_bf16 v[48:51], v[136:139], v[206:209], v[48:51]
	v_mfma_f32_16x16x32_bf16 v[44:47], v[160:163], v[206:209], v[44:47]
	v_mfma_f32_16x16x32_bf16 v[40:43], v[136:139], v[214:217], v[40:43]
	v_mfma_f32_16x16x32_bf16 v[36:39], v[160:163], v[214:217], v[36:39]
	v_mfma_f32_16x16x32_bf16 v[32:35], v[170:173], v[186:189], v[32:35]
	v_mfma_f32_16x16x32_bf16 v[28:31], v[178:181], v[186:189], v[28:31]
	v_mfma_f32_16x16x32_bf16 v[24:27], v[170:173], v[194:197], v[24:27]
	v_mfma_f32_16x16x32_bf16 v[20:23], v[178:181], v[194:197], v[20:23]
	v_mfma_f32_16x16x32_bf16 v[16:19], v[170:173], v[202:205], v[16:19]
	v_mfma_f32_16x16x32_bf16 v[12:15], v[178:181], v[202:205], v[12:15]
	v_mfma_f32_16x16x32_bf16 v[8:11], v[170:173], v[210:213], v[8:11]
	v_mfma_f32_16x16x32_bf16 v[2:5], v[178:181], v[210:213], v[4:7]
	v_mfma_f32_16x16x32_bf16 v[32:35], v[174:177], v[190:193], v[32:35]
	v_mfma_f32_16x16x32_bf16 v[28:31], v[182:185], v[190:193], v[28:31]
	v_mfma_f32_16x16x32_bf16 v[24:27], v[174:177], v[198:201], v[24:27]
	v_mfma_f32_16x16x32_bf16 v[20:23], v[182:185], v[198:201], v[20:23]
	v_mfma_f32_16x16x32_bf16 v[16:19], v[174:177], v[206:209], v[16:19]
	v_mfma_f32_16x16x32_bf16 v[12:15], v[182:185], v[206:209], v[12:15]
	v_mfma_f32_16x16x32_bf16 v[8:11], v[174:177], v[214:217], v[8:11]
	v_mfma_f32_16x16x32_bf16 v[2:5], v[182:185], v[214:217], v[2:5]
	s_barrier
; #define PG8_STAGE(bufoff, gbase, voff) do { _Pragma("unroll") for (int _i = 0; _i < 2; ++_i) \
;         __builtin_amdgcn_global_load_lds((const unsigned*)((const char*)(gbase) + (voff)[_i]), (PG8_LAS unsigned*)(lds + (bufoff) + ldsw + _i * 8192), 16, 0, 0); } while (0)
; #define PG8_LDA(dst, b, h) do { _Pragma("unroll") for (int m = 0; m < 4; ++m) _Pragma("unroll") for (int k = 0; k < 2; ++k) dst[m][k] = *(const PG8_LAS bf16x8*)(lds + PG8_SA(b, h) + aoff + m * 2048 + k * 1024); } while (0)
; #define PG8_LDB(dst, b, h) do { _Pragma("unroll") for (int n = 0; n < 2; ++n) _Pragma("unroll") for (int k = 0; k < 2; ++k) dst[n][k] = *(const PG8_LAS bf16x8*)(lds + PG8_SB(b, h) + boff + n * 2048 + k * 1024); } while (0)
; #define PG8_WAIT_V(n) asm volatile("s_waitcnt vmcnt(" #n ")" ::: "memory")
; #define PG8_WAIT_L(n) asm volatile("s_waitcnt lgkmcnt(" #n ")" ::: "memory")
; #define PG8_BAR __builtin_amdgcn_s_barrier()
; #define PG8_SCHED __builtin_amdgcn_sched_barrier(0)
; template <class Epi, class Sched, bool ALIGN_EPI = false, bool SP2 = false, bool F8 = false>
; __device__ __forceinline__ void gemm_phase(PG8_LAS unsigned char* lds, const int K, const Sched& S, const Epi& E, const int wave) {
;     ...
;         for (int t = 0; t < nt; t += 2) {
;             const bool last = (t == nt - 2);
;             const char* a1 = cA + (size_t)(t + 1) * kstep;
;             const char* a2 = last ? nA : cA + (size_t)(t + 2) * kstep; const char* b2 = last ? nB : cB + (size_t)(t + 2) * kstep;
;             const char* a3 = a2 + kstep; const char* b3 = b2 + kstep;
;     ...
;             PG8_LDB(B0, 1, 0); PG8_LDB(B1, 1, 1); PG8_SCHED; PG8_LDA(At, 1, 0); PG8_STAGE(PG8_SA(0, 1), a2 + hstep, voffA);
;             PG8_WAIT_V(8); PG8_WAIT_L(0); PG8_BAR; PG8_MMA(0, 0, At, B0); PG8_MMA(0, 1, At, B1); PG8_BAR; PG8_SCHED;
;             PG8_LDA(At, 1, 1); PG8_STAGE(PG8_SB(1, 0), b3, voffB); PG8_STAGE(PG8_SB(1, 1), b3 + hstep, voffB); PG8_STAGE(PG8_SA(1, 0), a3, voffA);
;             PG8_WAIT_V(8); PG8_WAIT_L(0); PG8_BAR; PG8_MMA(1, 0, At, B0); PG8_MMA(1, 1, At, B1); PG8_BAR; PG8_SCHED;
.Lmid_k1348:
	s_setprio 0
	s_add_i32 s42, 0, 0x18000
	v_add_u32_e32 v1, s42, v166
	s_add_i32 s43, 0, 0x1c000
	ds_read_b128 v[132:135], v1
	ds_read_b128 v[136:139], v1 offset:1024
	ds_read_b128 v[156:159], v1 offset:2048
	ds_read_b128 v[160:163], v1 offset:3072
	v_add_u32_e32 v1, s43, v166
	ds_read_b128 v[170:173], v1
	ds_read_b128 v[174:177], v1 offset:1024
	ds_read_b128 v[178:181], v1 offset:2048
	ds_read_b128 v[182:185], v1 offset:3072
	s_add_u32 s40, s40, 0x2b0000
	s_addc_u32 s41, s41, 0
	s_mov_b32 m0, s60
	ds_read_b128 v[186:189], v168 offset:32768
	ds_read_b128 v[190:193], v168 offset:33792
	ds_read_b128 v[194:197], v168 offset:34816
	ds_read_b128 v[198:201], v168 offset:35840
	ds_read_b128 v[202:205], v168 offset:36864
	ds_read_b128 v[206:209], v168 offset:37888
	ds_read_b128 v[210:213], v168 offset:38912
	ds_read_b128 v[214:217], v168 offset:39936
	global_load_lds_dwordx4 v140, s[40:41]
	s_mov_b32 m0, s61
	s_nop 0
	global_load_lds_dwordx4 v144, s[40:41]
	s_waitcnt vmcnt(8)
	s_waitcnt lgkmcnt(0)
	s_setprio 1
	s_barrier
	v_mfma_f32_16x16x32_bf16 v[128:131], v[132:135], v[186:189], v[128:131]
	v_mfma_f32_16x16x32_bf16 v[124:127], v[156:159], v[186:189], v[124:127]
	v_mfma_f32_16x16x32_bf16 v[120:123], v[132:135], v[194:197], v[120:123]
	v_mfma_f32_16x16x32_bf16 v[116:119], v[156:159], v[194:197], v[116:119]
	v_mfma_f32_16x16x32_bf16 v[112:115], v[132:135], v[202:205], v[112:115]
	v_mfma_f32_16x16x32_bf16 v[108:111], v[156:159], v[202:205], v[108:111]
	v_mfma_f32_16x16x32_bf16 v[104:107], v[132:135], v[210:213], v[104:107]
	v_mfma_f32_16x16x32_bf16 v[100:103], v[156:159], v[210:213], v[100:103]
	v_mfma_f32_16x16x32_bf16 v[128:131], v[136:139], v[190:193], v[128:131]
	v_mfma_f32_16x16x32_bf16 v[124:127], v[160:163], v[190:193], v[124:127]
	v_mfma_f32_16x16x32_bf16 v[120:123], v[136:139], v[198:201], v[120:123]
	v_mfma_f32_16x16x32_bf16 v[116:119], v[160:163], v[198:201], v[116:119]
	v_mfma_f32_16x16x32_bf16 v[112:115], v[136:139], v[206:209], v[112:115]
	v_mfma_f32_16x16x32_bf16 v[108:111], v[160:163], v[206:209], v[108:111]
	v_mfma_f32_16x16x32_bf16 v[104:107], v[136:139], v[214:217], v[104:107]
	v_mfma_f32_16x16x32_bf16 v[100:103], v[160:163], v[214:217], v[100:103]
	v_mfma_f32_16x16x32_bf16 v[96:99], v[170:173], v[186:189], v[96:99]
	v_mfma_f32_16x16x32_bf16 v[92:95], v[178:181], v[186:189], v[92:95]
	v_mfma_f32_16x16x32_bf16 v[88:91], v[170:173], v[194:197], v[88:91]
	v_mfma_f32_16x16x32_bf16 v[84:87], v[178:181], v[194:197], v[84:87]
	v_mfma_f32_16x16x32_bf16 v[80:83], v[170:173], v[202:205], v[80:83]
	v_mfma_f32_16x16x32_bf16 v[76:79], v[178:181], v[202:205], v[76:79]
	v_mfma_f32_16x16x32_bf16 v[72:75], v[170:173], v[210:213], v[72:75]
	v_mfma_f32_16x16x32_bf16 v[68:71], v[178:181], v[210:213], v[68:71]
	v_mfma_f32_16x16x32_bf16 v[96:99], v[174:177], v[190:193], v[96:99]
	v_mfma_f32_16x16x32_bf16 v[92:95], v[182:185], v[190:193], v[92:95]
	v_mfma_f32_16x16x32_bf16 v[88:91], v[174:177], v[198:201], v[88:91]
	v_mfma_f32_16x16x32_bf16 v[84:87], v[182:185], v[198:201], v[84:87]
	v_mfma_f32_16x16x32_bf16 v[80:83], v[174:177], v[206:209], v[80:83]
	v_mfma_f32_16x16x32_bf16 v[76:79], v[182:185], v[206:209], v[76:79]
	v_mfma_f32_16x16x32_bf16 v[72:75], v[174:177], v[214:217], v[72:75]
	v_mfma_f32_16x16x32_bf16 v[68:71], v[182:185], v[214:217], v[68:71]
	s_barrier
	s_setprio 0
	s_add_i32 s40, s42, s57
	s_mov_b32 m0, s40
	ds_read_b128 v[186:189], v168 offset:49152
	ds_read_b128 v[190:193], v168 offset:50176
	ds_read_b128 v[194:197], v168 offset:51200
	ds_read_b128 v[198:201], v168 offset:52224
	ds_read_b128 v[202:205], v168 offset:53248
	ds_read_b128 v[206:209], v168 offset:54272
	ds_read_b128 v[210:213], v168 offset:55296
	ds_read_b128 v[214:217], v168 offset:56320
	global_load_lds_dwordx4 v142, s[38:39]
	s_add_i32 m0, s40, 0x2000
	s_nop 0
	global_load_lds_dwordx4 v146, s[38:39]
	s_add_u32 s38, s38, 0x2b0000
	s_addc_u32 s39, s39, 0
	s_add_i32 s40, s43, s57
	s_mov_b32 m0, s40
	s_nop 0
	global_load_lds_dwordx4 v142, s[38:39]
	s_add_i32 m0, s40, 0x2000
	s_nop 0
	global_load_lds_dwordx4 v146, s[38:39]
	s_mov_b32 m0, s65
	s_nop 0
	global_load_lds_dwordx4 v140, s[8:9]
	s_mov_b32 m0, s66
	s_nop 0
	global_load_lds_dwordx4 v144, s[8:9]
	s_waitcnt vmcnt(8)
	s_waitcnt lgkmcnt(0)
	s_setprio 1
	s_barrier
	v_mfma_f32_16x16x32_bf16 v[64:67], v[132:135], v[186:189], v[64:67]
	v_mfma_f32_16x16x32_bf16 v[60:63], v[156:159], v[186:189], v[60:63]
	v_mfma_f32_16x16x32_bf16 v[56:59], v[132:135], v[194:197], v[56:59]
	v_mfma_f32_16x16x32_bf16 v[52:55], v[156:159], v[194:197], v[52:55]
	v_mfma_f32_16x16x32_bf16 v[48:51], v[132:135], v[202:205], v[48:51]
	v_mfma_f32_16x16x32_bf16 v[44:47], v[156:159], v[202:205], v[44:47]
	v_mfma_f32_16x16x32_bf16 v[40:43], v[132:135], v[210:213], v[40:43]
	v_mfma_f32_16x16x32_bf16 v[36:39], v[156:159], v[210:213], v[36:39]
	v_mfma_f32_16x16x32_bf16 v[64:67], v[136:139], v[190:193], v[64:67]
	v_mfma_f32_16x16x32_bf16 v[60:63], v[160:163], v[190:193], v[60:63]
	v_mfma_f32_16x16x32_bf16 v[56:59], v[136:139], v[198:201], v[56:59]
	v_mfma_f32_16x16x32_bf16 v[52:55], v[160:163], v[198:201], v[52:55]
	v_mfma_f32_16x16x32_bf16 v[48:51], v[136:139], v[206:209], v[48:51]
	v_mfma_f32_16x16x32_bf16 v[44:47], v[160:163], v[206:209], v[44:47]
	v_mfma_f32_16x16x32_bf16 v[40:43], v[136:139], v[214:217], v[40:43]
	v_mfma_f32_16x16x32_bf16 v[36:39], v[160:163], v[214:217], v[36:39]
	v_mfma_f32_16x16x32_bf16 v[32:35], v[170:173], v[186:189], v[32:35]
	v_mfma_f32_16x16x32_bf16 v[28:31], v[178:181], v[186:189], v[28:31]
	v_mfma_f32_16x16x32_bf16 v[24:27], v[170:173], v[194:197], v[24:27]
	v_mfma_f32_16x16x32_bf16 v[20:23], v[178:181], v[194:197], v[20:23]
	v_mfma_f32_16x16x32_bf16 v[16:19], v[170:173], v[202:205], v[16:19]
	v_mfma_f32_16x16x32_bf16 v[12:15], v[178:181], v[202:205], v[12:15]
	v_mfma_f32_16x16x32_bf16 v[6:9], v[170:173], v[210:213], v[8:11]
	v_mfma_f32_16x16x32_bf16 v[2:5], v[178:181], v[210:213], v[2:5]
	v_mfma_f32_16x16x32_bf16 v[32:35], v[174:177], v[190:193], v[32:35]
	v_mfma_f32_16x16x32_bf16 v[28:31], v[182:185], v[190:193], v[28:31]
	v_mfma_f32_16x16x32_bf16 v[24:27], v[174:177], v[198:201], v[24:27]
	v_mfma_f32_16x16x32_bf16 v[20:23], v[182:185], v[198:201], v[20:23]
	v_mfma_f32_16x16x32_bf16 v[16:19], v[174:177], v[206:209], v[16:19]
	v_mfma_f32_16x16x32_bf16 v[12:15], v[182:185], v[206:209], v[12:15]
	v_mfma_f32_16x16x32_bf16 v[8:11], v[174:177], v[214:217], v[6:9]
	v_mfma_f32_16x16x32_bf16 v[4:7], v[182:185], v[214:217], v[2:5]
	s_barrier
	s_setprio 0
	s_add_u32 s83, s83, 0x100
	s_addc_u32 s84, s84, 0
	s_add_u32 s85, s85, 0x100
	s_addc_u32 s86, s86, 0
	s_add_u32 s6, s6, 0x100
	s_addc_u32 s7, s7, 0
	s_cmp_ge_i32 s87, s56
	s_mov_b32 s8, s87
	s_cbranch_scc0 .LBB0_1348
